# staging loads of 8 GEMM loops re-issued right after the LDS write that frees their registers (write_k, load_k pairs, counted vmcnt)
# speedup vs baseline: 1.0058x; 1.0014x over previous
; DI f32x4 mfma16(bf16x8 a, bf16x8 b, f32x4 c) { return __builtin_amdgcn_mfma_f32_16x16x32_bf16(a, b, c, 0, 0, 0); }
; template <int MI, int NJ, bool SWAP, class AP, class BP>
; DI void gemm_main(f32x4 (&acc)[MI][NJ], const AP& ap, int a_kstep, const BP& bp, int b_kstep, int nk, bf16_t* smem) {
;     ...
;   auto gload = [&](int kt) {
;     const bf16_t* ab = ap.base + (size_t)kt * a_kstep; const bf16_t* bb = bp.base + (size_t)kt * b_kstep;
; #pragma unroll
;     for (int i = 0; i < CA; ++i) ra[i] = *(const u32x4*)(ab + pa[i]);
; #pragma unroll
;     for (int i = 0; i < CB; ++i) rb[i] = *(const u32x4*)(bb + pb[i]);
;   };
;   auto sstore = [&](int buf) {
;     bf16_t* As = smem + buf * L::STAGE; bf16_t* Bs = As + L::A_ELEMS;
; #pragma unroll
;     for (int i = 0; i < CA; ++i) { const int c = tid + NTHR * i; *(u32x4*)(As + (c >> 3) * LDT + (c & 7) * 8) = oka[i] ? ra[i] : (u32x4){0u, 0u, 0u, 0u}; }
; #pragma unroll
;     for (int i = 0; i < CB; ++i) { const int c = tid + NTHR * i; *(u32x4*)(Bs + (c >> 3) * LDT + (c & 7) * 8) = rb[i]; }
;   };
;   gload(0); sstore(0); gload(nk > 1 ? 1 : 0); __syncthreads();
; #pragma unroll 1
;   for (int kt = 0; kt < nk; ++kt) {
;     const int buf = kt & 1;
;     sstore(buf ^ 1);
;     gload(kt + 2 < nk ? kt + 2 : nk - 1);
;     __builtin_amdgcn_sched_barrier(0);
;     const bf16_t* As = smem + buf * L::STAGE + (wm * 16 * MI + l15) * LDT + quad * 8;
;     const bf16_t* Bs = smem + buf * L::STAGE + L::A_ELEMS + (wn * 16 * NJ + l15) * LDT + quad * 8;
; #pragma unroll
;     for (int ks = 0; ks < 2; ++ks) {
;       if (MI * NJ >= 32 && ks == 1) asm volatile("" ::: "memory");
;       bf16x8 b[NJ];
; #pragma unroll
;       for (int j = 0; j < NJ; ++j) b[j] = *(const bf16x8*)(Bs + j * 16 * LDT + ks * 32);
; #pragma unroll
;       for (int i = 0; i < MI; ++i) {
;         const bf16x8 a = *(const bf16x8*)(As + i * 16 * LDT + ks * 32);
; #pragma unroll
;         for (int j = 0; j < NJ; ++j) acc[i][j] = SWAP ? mfma16(b[j], a, acc[i][j]) : mfma16(a, b[j], acc[i][j]);
;       }
;     }
;     __syncthreads();
;   }
.Lgm0_main:
	ds_read_b128 v[242:245], v176 offset:4608
	s_waitcnt lgkmcnt(4)
	v_mfma_f32_16x16x32_bf16 v[124:127], v[178:181], v[212:215], v[124:127]
	s_waitcnt lgkmcnt(3)
	v_mfma_f32_16x16x32_bf16 v[120:123], v[200:203], v[212:215], v[120:123]
	s_waitcnt lgkmcnt(2)
	v_mfma_f32_16x16x32_bf16 v[116:119], v[204:207], v[212:215], v[116:119]
	s_and_b32 s5, s4, 1
	s_min_u32 s6, s4, 13
	s_xor_b32 s7, s5, 1
	s_lshl_b32 s33, s6, 7
	s_mul_i32 s7, s7, 0x12000
	s_add_u32 s6, s0, s33
	v_add3_u32 v250, s7, v171, v169
	v_add3_u32 v251, s7, v173, v169
	v_add3_u32 v252, s7, v174, v169
	v_add3_u32 v253, s7, v175, v169
	s_addc_u32 s7, s1, 0
	s_waitcnt vmcnt(7)
	ds_write_b128 v250, v[128:131]
	s_waitcnt lgkmcnt(2)
	v_mfma_f32_16x16x32_bf16 v[112:115], v[208:211], v[212:215], v[112:115]
	ds_read_b128 v[246:249], v176 offset:6912
	v_mfma_f32_16x16x32_bf16 v[108:111], v[178:181], v[216:219], v[108:111]
	v_lshl_add_u64 v[128:129], s[6:7], 0, v[160:161]
	s_nop 0
	global_load_dwordx4 v[128:131], v[128:129], off offset:256
	v_mfma_f32_16x16x32_bf16 v[104:107], v[200:203], v[216:219], v[104:107]
	v_mfma_f32_16x16x32_bf16 v[100:103], v[204:207], v[216:219], v[100:103]
	v_mfma_f32_16x16x32_bf16 v[96:99], v[208:211], v[216:219], v[96:99]
	ds_read_b128 v[212:215], v176 offset:9216
	s_waitcnt lgkmcnt(3)
	v_mfma_f32_16x16x32_bf16 v[92:95], v[178:181], v[242:245], v[92:95]
	s_waitcnt vmcnt(7)
	ds_write_b128 v251, v[132:135]
	v_mfma_f32_16x16x32_bf16 v[88:91], v[200:203], v[242:245], v[88:91]
	v_mfma_f32_16x16x32_bf16 v[84:87], v[204:207], v[242:245], v[84:87]
	v_lshl_add_u64 v[132:133], s[6:7], 0, v[162:163]
	s_nop 0
	global_load_dwordx4 v[132:135], v[132:133], off offset:256
	v_mfma_f32_16x16x32_bf16 v[80:83], v[208:211], v[242:245], v[80:83]
	ds_read_b128 v[216:219], v176 offset:11520
	s_waitcnt lgkmcnt(3)
	v_mfma_f32_16x16x32_bf16 v[76:79], v[178:181], v[246:249], v[76:79]
	v_mfma_f32_16x16x32_bf16 v[72:75], v[200:203], v[246:249], v[72:75]
	v_mfma_f32_16x16x32_bf16 v[68:71], v[204:207], v[246:249], v[68:71]
	s_waitcnt vmcnt(7)
	ds_write_b128 v252, v[136:139]
	v_mfma_f32_16x16x32_bf16 v[64:67], v[208:211], v[246:249], v[64:67]
	ds_read_b128 v[242:245], v176 offset:13824
	s_waitcnt lgkmcnt(4)
	v_mfma_f32_16x16x32_bf16 v[60:63], v[178:181], v[212:215], v[60:63]
	v_lshl_add_u64 v[136:137], s[6:7], 0, v[164:165]
	s_nop 0
	global_load_dwordx4 v[136:139], v[136:137], off offset:256
	v_mfma_f32_16x16x32_bf16 v[56:59], v[200:203], v[212:215], v[56:59]
	v_mfma_f32_16x16x32_bf16 v[52:55], v[204:207], v[212:215], v[52:55]
	v_mfma_f32_16x16x32_bf16 v[48:51], v[208:211], v[212:215], v[48:51]
	ds_read_b128 v[246:249], v176 offset:16128
	s_waitcnt lgkmcnt(3)
	v_mfma_f32_16x16x32_bf16 v[44:47], v[178:181], v[216:219], v[44:47]
	s_waitcnt vmcnt(7)
	ds_write_b128 v253, v[140:143]
	v_mfma_f32_16x16x32_bf16 v[40:43], v[200:203], v[216:219], v[40:43]
	v_mfma_f32_16x16x32_bf16 v[36:39], v[204:207], v[216:219], v[36:39]
	v_lshl_add_u64 v[140:141], s[6:7], 0, v[166:167]
	s_nop 0
	global_load_dwordx4 v[140:143], v[140:141], off offset:256
	v_mfma_f32_16x16x32_bf16 v[32:35], v[208:211], v[216:219], v[32:35]
	ds_read_b128 v[212:215], v176 offset:64
	s_waitcnt lgkmcnt(3)
	v_mfma_f32_16x16x32_bf16 v[28:31], v[178:181], v[242:245], v[28:31]
	v_mfma_f32_16x16x32_bf16 v[24:27], v[200:203], v[242:245], v[24:27]
	v_mfma_f32_16x16x32_bf16 v[20:23], v[204:207], v[242:245], v[20:23]
	s_waitcnt vmcnt(7)
	ds_write_b128 v250, v[144:147] offset:36864
	v_mfma_f32_16x16x32_bf16 v[16:19], v[208:211], v[242:245], v[16:19]
	ds_read_b128 v[216:219], v176 offset:2368
	s_waitcnt lgkmcnt(4)
	v_mfma_f32_16x16x32_bf16 v[12:15], v[178:181], v[246:249], v[12:15]
	ds_read_b128 v[178:181], v182 offset:36928
	s_add_u32 s6, s2, s33
	s_addc_u32 s7, s3, 0
	v_lshl_add_u64 v[144:145], s[6:7], 0, v[160:161]
	s_nop 0
	global_load_dwordx4 v[144:147], v[144:145], off offset:256
	v_mfma_f32_16x16x32_bf16 v[8:11], v[200:203], v[246:249], v[8:11]
	ds_read_b128 v[200:203], v182 offset:39232
	v_mfma_f32_16x16x32_bf16 v[0:3], v[204:207], v[246:249], v[0:3]
	ds_read_b128 v[204:207], v182 offset:41536
	v_mfma_f32_16x16x32_bf16 v[4:7], v[208:211], v[246:249], v[4:7]
	ds_read_b128 v[208:211], v182 offset:43840
	ds_read_b128 v[242:245], v176 offset:4672
	s_waitcnt lgkmcnt(4)
	v_mfma_f32_16x16x32_bf16 v[124:127], v[178:181], v[212:215], v[124:127]
	s_waitcnt vmcnt(7)
	ds_write_b128 v251, v[148:151] offset:36864
	s_waitcnt lgkmcnt(4)
	v_mfma_f32_16x16x32_bf16 v[120:123], v[200:203], v[212:215], v[120:123]
	s_waitcnt lgkmcnt(3)
	v_mfma_f32_16x16x32_bf16 v[116:119], v[204:207], v[212:215], v[116:119]
	v_lshl_add_u64 v[148:149], s[6:7], 0, v[162:163]
	s_nop 0
	global_load_dwordx4 v[148:151], v[148:149], off offset:256
	s_waitcnt lgkmcnt(2)
	v_mfma_f32_16x16x32_bf16 v[112:115], v[208:211], v[212:215], v[112:115]
	ds_read_b128 v[246:249], v176 offset:6976
	v_mfma_f32_16x16x32_bf16 v[108:111], v[178:181], v[216:219], v[108:111]
	v_mfma_f32_16x16x32_bf16 v[104:107], v[200:203], v[216:219], v[104:107]
	v_mfma_f32_16x16x32_bf16 v[100:103], v[204:207], v[216:219], v[100:103]
	s_waitcnt vmcnt(7)
	ds_write_b128 v252, v[152:155] offset:36864
	v_mfma_f32_16x16x32_bf16 v[96:99], v[208:211], v[216:219], v[96:99]
	ds_read_b128 v[212:215], v176 offset:9280
	s_waitcnt lgkmcnt(4)
	v_mfma_f32_16x16x32_bf16 v[92:95], v[178:181], v[242:245], v[92:95]
	v_lshl_add_u64 v[152:153], s[6:7], 0, v[164:165]
	s_nop 0
	global_load_dwordx4 v[152:155], v[152:153], off offset:256
	v_mfma_f32_16x16x32_bf16 v[88:91], v[200:203], v[242:245], v[88:91]
	v_mfma_f32_16x16x32_bf16 v[84:87], v[204:207], v[242:245], v[84:87]
	v_mfma_f32_16x16x32_bf16 v[80:83], v[208:211], v[242:245], v[80:83]
	ds_read_b128 v[216:219], v176 offset:11584
	s_waitcnt lgkmcnt(3)
	v_mfma_f32_16x16x32_bf16 v[76:79], v[178:181], v[246:249], v[76:79]
	s_waitcnt vmcnt(7)
	ds_write_b128 v253, v[156:159] offset:36864
	v_mfma_f32_16x16x32_bf16 v[72:75], v[200:203], v[246:249], v[72:75]
	v_mfma_f32_16x16x32_bf16 v[68:71], v[204:207], v[246:249], v[68:71]
	v_lshl_add_u64 v[156:157], s[6:7], 0, v[166:167]
	s_nop 0
	global_load_dwordx4 v[156:159], v[156:157], off offset:256
	v_mfma_f32_16x16x32_bf16 v[64:67], v[208:211], v[246:249], v[64:67]
	ds_read_b128 v[242:245], v176 offset:13888
	s_waitcnt lgkmcnt(3)
	v_mfma_f32_16x16x32_bf16 v[60:63], v[178:181], v[212:215], v[60:63]
	v_mfma_f32_16x16x32_bf16 v[56:59], v[200:203], v[212:215], v[56:59]
	v_mfma_f32_16x16x32_bf16 v[52:55], v[204:207], v[212:215], v[52:55]
	v_mfma_f32_16x16x32_bf16 v[48:51], v[208:211], v[212:215], v[48:51]
	ds_read_b128 v[246:249], v176 offset:16192
	s_waitcnt lgkmcnt(3)
	v_mfma_f32_16x16x32_bf16 v[44:47], v[178:181], v[216:219], v[44:47]
	v_mfma_f32_16x16x32_bf16 v[40:43], v[200:203], v[216:219], v[40:43]
	v_mfma_f32_16x16x32_bf16 v[36:39], v[204:207], v[216:219], v[36:39]
	v_mfma_f32_16x16x32_bf16 v[32:35], v[208:211], v[216:219], v[32:35]
	s_waitcnt lgkmcnt(0)
	s_barrier
; DI f32x4 mfma16(bf16x8 a, bf16x8 b, f32x4 c) { return __builtin_amdgcn_mfma_f32_16x16x32_bf16(a, b, c, 0, 0, 0); }
; template <int MI, int NJ, bool SWAP, class AP, class BP>
; DI void gemm_main(f32x4 (&acc)[MI][NJ], const AP& ap, int a_kstep, const BP& bp, int b_kstep, int nk, bf16_t* smem) {
;     ...
;   for (int kt = 0; kt < nk; ++kt) {
;     const int buf = kt & 1;
;     sstore(buf ^ 1);
;     gload(kt + 2 < nk ? kt + 2 : nk - 1);
;     __builtin_amdgcn_sched_barrier(0);
;     const bf16_t* As = smem + buf * L::STAGE + (wm * 16 * MI + l15) * LDT + quad * 8;
;     const bf16_t* Bs = smem + buf * L::STAGE + L::A_ELEMS + (wn * 16 * NJ + l15) * LDT + quad * 8;
; #pragma unroll
;     for (int ks = 0; ks < 2; ++ks) {
;       if (MI * NJ >= 32 && ks == 1) asm volatile("" ::: "memory");
;       bf16x8 b[NJ];
; #pragma unroll
;       for (int j = 0; j < NJ; ++j) b[j] = *(const bf16x8*)(Bs + j * 16 * LDT + ks * 32);
; #pragma unroll
;       for (int i = 0; i < MI; ++i) {
;         const bf16x8 a = *(const bf16x8*)(As + i * 16 * LDT + ks * 32);
; #pragma unroll
;         for (int j = 0; j < NJ; ++j) acc[i][j] = SWAP ? mfma16(b[j], a, acc[i][j]) : mfma16(a, b[j], acc[i][j]);
;       }
	s_add_i32 s4, s4, 1
	s_cmp_lg_u32 s4, 16
	s_cbranch_scc0 .Lgm0_exit
	s_and_b32 s98, s4, 1
	s_mul_i32 s98, s98, 0x12000
	v_add3_u32 v182, s98, v168, v172
	v_add3_u32 v176, s98, v170, v172
	ds_read_b128 v[212:215], v176
	ds_read_b128 v[216:219], v176 offset:2304
	v_mfma_f32_16x16x32_bf16 v[28:31], v[178:181], v[242:245], v[28:31]
	v_mfma_f32_16x16x32_bf16 v[12:15], v[178:181], v[246:249], v[12:15]
	ds_read_b128 v[178:181], v182 offset:36864
	v_mfma_f32_16x16x32_bf16 v[24:27], v[200:203], v[242:245], v[24:27]
	v_mfma_f32_16x16x32_bf16 v[8:11], v[200:203], v[246:249], v[8:11]
	ds_read_b128 v[200:203], v182 offset:39168
	v_mfma_f32_16x16x32_bf16 v[20:23], v[204:207], v[242:245], v[20:23]
	v_mfma_f32_16x16x32_bf16 v[0:3], v[204:207], v[246:249], v[0:3]
	ds_read_b128 v[204:207], v182 offset:41472
	v_mfma_f32_16x16x32_bf16 v[16:19], v[208:211], v[242:245], v[16:19]
	v_mfma_f32_16x16x32_bf16 v[4:7], v[208:211], v[246:249], v[4:7]
	ds_read_b128 v[208:211], v182 offset:43776
	s_branch .Lgm0_main

; DI f32x4 mfma16(bf16x8 a, bf16x8 b, f32x4 c) { return __builtin_amdgcn_mfma_f32_16x16x32_bf16(a, b, c, 0, 0, 0); }
; template <int MI, int NJ, bool SWAP, class AP, class BP>
; DI void gemm_main(f32x4 (&acc)[MI][NJ], const AP& ap, int a_kstep, const BP& bp, int b_kstep, int nk, bf16_t* smem) {
;     ...
;   auto gload = [&](int kt) {
;     const bf16_t* ab = ap.base + (size_t)kt * a_kstep; const bf16_t* bb = bp.base + (size_t)kt * b_kstep;
; #pragma unroll
;     for (int i = 0; i < CA; ++i) ra[i] = *(const u32x4*)(ab + pa[i]);
; #pragma unroll
;     for (int i = 0; i < CB; ++i) rb[i] = *(const u32x4*)(bb + pb[i]);
;   };
;   auto sstore = [&](int buf) {
;     bf16_t* As = smem + buf * L::STAGE; bf16_t* Bs = As + L::A_ELEMS;
; #pragma unroll
;     for (int i = 0; i < CA; ++i) { const int c = tid + NTHR * i; *(u32x4*)(As + (c >> 3) * LDT + (c & 7) * 8) = oka[i] ? ra[i] : (u32x4){0u, 0u, 0u, 0u}; }
; #pragma unroll
;     for (int i = 0; i < CB; ++i) { const int c = tid + NTHR * i; *(u32x4*)(Bs + (c >> 3) * LDT + (c & 7) * 8) = rb[i]; }
;   };
;   gload(0); sstore(0); gload(nk > 1 ? 1 : 0); __syncthreads();
; #pragma unroll 1
;   for (int kt = 0; kt < nk; ++kt) {
;     const int buf = kt & 1;
;     sstore(buf ^ 1);
;     gload(kt + 2 < nk ? kt + 2 : nk - 1);
;     __builtin_amdgcn_sched_barrier(0);
;     const bf16_t* As = smem + buf * L::STAGE + (wm * 16 * MI + l15) * LDT + quad * 8;
;     const bf16_t* Bs = smem + buf * L::STAGE + L::A_ELEMS + (wn * 16 * NJ + l15) * LDT + quad * 8;
; #pragma unroll
;     for (int ks = 0; ks < 2; ++ks) {
;       if (MI * NJ >= 32 && ks == 1) asm volatile("" ::: "memory");
;       bf16x8 b[NJ];
; #pragma unroll
;       for (int j = 0; j < NJ; ++j) b[j] = *(const bf16x8*)(Bs + j * 16 * LDT + ks * 32);
; #pragma unroll
;       for (int i = 0; i < MI; ++i) {
;         const bf16x8 a = *(const bf16x8*)(As + i * 16 * LDT + ks * 32);
; #pragma unroll
;         for (int j = 0; j < NJ; ++j) acc[i][j] = SWAP ? mfma16(b[j], a, acc[i][j]) : mfma16(a, b[j], acc[i][j]);
;       }
;     }
;     __syncthreads();
;   }
.Lgm1_main:
	ds_read_b128 v[242:245], v176 offset:4608
	s_waitcnt lgkmcnt(4)
	v_mfma_f32_16x16x32_bf16 v[124:127], v[212:215], v[178:181], v[124:127]
	s_waitcnt lgkmcnt(3)
	v_mfma_f32_16x16x32_bf16 v[120:123], v[212:215], v[200:203], v[120:123]
	s_waitcnt lgkmcnt(2)
	v_mfma_f32_16x16x32_bf16 v[116:119], v[212:215], v[204:207], v[116:119]
	s_and_b32 s5, s4, 1
	s_min_u32 s6, s4, 13
	s_xor_b32 s7, s5, 1
	s_lshl_b32 s33, s6, 7
	v_lshlrev_b32_e32 v250, 1, v168
	v_lshlrev_b32_e32 v251, 1, v171
	v_lshlrev_b32_e32 v252, 1, v172
	v_lshlrev_b32_e32 v253, 1, v173
	s_mul_i32 s7, s7, 0x12000
	s_add_u32 s6, s0, s33
	v_add3_u32 v250, s7, v250, v170
	v_add3_u32 v251, s7, v251, v170
	v_add3_u32 v252, s7, v252, v170
	v_add3_u32 v253, s7, v253, v170
	s_addc_u32 s7, s1, 0
	s_waitcnt vmcnt(7)
	ds_write_b128 v250, v[128:131]
	s_waitcnt lgkmcnt(2)
	v_mfma_f32_16x16x32_bf16 v[112:115], v[212:215], v[208:211], v[112:115]
	ds_read_b128 v[246:249], v176 offset:6912
	v_mfma_f32_16x16x32_bf16 v[108:111], v[216:219], v[178:181], v[108:111]
	v_lshl_add_u64 v[128:129], s[6:7], 0, v[160:161]
	s_nop 0
	global_load_dwordx4 v[128:131], v[128:129], off offset:256
	v_mfma_f32_16x16x32_bf16 v[104:107], v[216:219], v[200:203], v[104:107]
	v_mfma_f32_16x16x32_bf16 v[100:103], v[216:219], v[204:207], v[100:103]
	v_mfma_f32_16x16x32_bf16 v[96:99], v[216:219], v[208:211], v[96:99]
	ds_read_b128 v[212:215], v176 offset:9216
	s_waitcnt lgkmcnt(3)
	v_mfma_f32_16x16x32_bf16 v[92:95], v[242:245], v[178:181], v[92:95]
	s_waitcnt vmcnt(7)
	ds_write_b128 v251, v[132:135]
	v_mfma_f32_16x16x32_bf16 v[88:91], v[242:245], v[200:203], v[88:91]
	v_mfma_f32_16x16x32_bf16 v[84:87], v[242:245], v[204:207], v[84:87]
	v_lshl_add_u64 v[132:133], s[6:7], 0, v[162:163]
	s_nop 0
	global_load_dwordx4 v[132:135], v[132:133], off offset:256
	v_mfma_f32_16x16x32_bf16 v[80:83], v[242:245], v[208:211], v[80:83]
	ds_read_b128 v[216:219], v176 offset:11520
	s_waitcnt lgkmcnt(3)
	v_mfma_f32_16x16x32_bf16 v[76:79], v[246:249], v[178:181], v[76:79]
	v_mfma_f32_16x16x32_bf16 v[72:75], v[246:249], v[200:203], v[72:75]
	v_mfma_f32_16x16x32_bf16 v[68:71], v[246:249], v[204:207], v[68:71]
	s_waitcnt vmcnt(7)
	ds_write_b128 v252, v[136:139]
	v_mfma_f32_16x16x32_bf16 v[64:67], v[246:249], v[208:211], v[64:67]
	ds_read_b128 v[242:245], v176 offset:13824
	s_waitcnt lgkmcnt(4)
	v_mfma_f32_16x16x32_bf16 v[60:63], v[212:215], v[178:181], v[60:63]
	v_lshl_add_u64 v[136:137], s[6:7], 0, v[164:165]
	s_nop 0
	global_load_dwordx4 v[136:139], v[136:137], off offset:256
	v_mfma_f32_16x16x32_bf16 v[56:59], v[212:215], v[200:203], v[56:59]
	v_mfma_f32_16x16x32_bf16 v[52:55], v[212:215], v[204:207], v[52:55]
	v_mfma_f32_16x16x32_bf16 v[48:51], v[212:215], v[208:211], v[48:51]
	ds_read_b128 v[246:249], v176 offset:16128
	s_waitcnt lgkmcnt(3)
	v_mfma_f32_16x16x32_bf16 v[44:47], v[216:219], v[178:181], v[44:47]
	s_waitcnt vmcnt(7)
	ds_write_b128 v253, v[140:143]
	v_mfma_f32_16x16x32_bf16 v[40:43], v[216:219], v[200:203], v[40:43]
	v_mfma_f32_16x16x32_bf16 v[36:39], v[216:219], v[204:207], v[36:39]
	v_lshl_add_u64 v[140:141], s[6:7], 0, v[166:167]
	s_nop 0
	global_load_dwordx4 v[140:143], v[140:141], off offset:256
	v_mfma_f32_16x16x32_bf16 v[32:35], v[216:219], v[208:211], v[32:35]
	ds_read_b128 v[212:215], v176 offset:64
	s_waitcnt lgkmcnt(3)
	v_mfma_f32_16x16x32_bf16 v[28:31], v[242:245], v[178:181], v[28:31]
	v_mfma_f32_16x16x32_bf16 v[24:27], v[242:245], v[200:203], v[24:27]
	v_mfma_f32_16x16x32_bf16 v[20:23], v[242:245], v[204:207], v[20:23]
	s_waitcnt vmcnt(7)
	ds_write_b128 v250, v[144:147] offset:36864
	v_mfma_f32_16x16x32_bf16 v[16:19], v[242:245], v[208:211], v[16:19]
	ds_read_b128 v[216:219], v176 offset:2368
	s_waitcnt lgkmcnt(4)
	v_mfma_f32_16x16x32_bf16 v[8:11], v[246:249], v[178:181], v[8:11]
	ds_read_b128 v[178:181], v182 offset:36928
	s_add_u32 s6, s2, s33
	s_addc_u32 s7, s3, 0
	v_lshl_add_u64 v[144:145], s[6:7], 0, v[160:161]
	s_nop 0
	global_load_dwordx4 v[144:147], v[144:145], off offset:256
	v_mfma_f32_16x16x32_bf16 v[4:7], v[246:249], v[200:203], v[4:7]
	ds_read_b128 v[200:203], v182 offset:39232
	v_mfma_f32_16x16x32_bf16 v[0:3], v[246:249], v[204:207], v[0:3]
	ds_read_b128 v[204:207], v182 offset:41536
	v_mfma_f32_16x16x32_bf16 v[12:15], v[246:249], v[208:211], v[12:15]
	ds_read_b128 v[208:211], v182 offset:43840
	ds_read_b128 v[242:245], v176 offset:4672
	s_waitcnt lgkmcnt(4)
	v_mfma_f32_16x16x32_bf16 v[124:127], v[212:215], v[178:181], v[124:127]
	s_waitcnt vmcnt(7)
	ds_write_b128 v251, v[148:151] offset:36864
	s_waitcnt lgkmcnt(4)
	v_mfma_f32_16x16x32_bf16 v[120:123], v[212:215], v[200:203], v[120:123]
	s_waitcnt lgkmcnt(3)
	v_mfma_f32_16x16x32_bf16 v[116:119], v[212:215], v[204:207], v[116:119]
	v_lshl_add_u64 v[148:149], s[6:7], 0, v[162:163]
	s_nop 0
	global_load_dwordx4 v[148:151], v[148:149], off offset:256
	s_waitcnt lgkmcnt(2)
	v_mfma_f32_16x16x32_bf16 v[112:115], v[212:215], v[208:211], v[112:115]
	ds_read_b128 v[246:249], v176 offset:6976
	v_mfma_f32_16x16x32_bf16 v[108:111], v[216:219], v[178:181], v[108:111]
	v_mfma_f32_16x16x32_bf16 v[104:107], v[216:219], v[200:203], v[104:107]
	v_mfma_f32_16x16x32_bf16 v[100:103], v[216:219], v[204:207], v[100:103]
	s_waitcnt vmcnt(7)
	ds_write_b128 v252, v[152:155] offset:36864
	v_mfma_f32_16x16x32_bf16 v[96:99], v[216:219], v[208:211], v[96:99]
	ds_read_b128 v[212:215], v176 offset:9280
	s_waitcnt lgkmcnt(4)
	v_mfma_f32_16x16x32_bf16 v[92:95], v[242:245], v[178:181], v[92:95]
	v_lshl_add_u64 v[152:153], s[6:7], 0, v[164:165]
	s_nop 0
	global_load_dwordx4 v[152:155], v[152:153], off offset:256
	v_mfma_f32_16x16x32_bf16 v[88:91], v[242:245], v[200:203], v[88:91]
	v_mfma_f32_16x16x32_bf16 v[84:87], v[242:245], v[204:207], v[84:87]
	v_mfma_f32_16x16x32_bf16 v[80:83], v[242:245], v[208:211], v[80:83]
	ds_read_b128 v[216:219], v176 offset:11584
	s_waitcnt lgkmcnt(3)
	v_mfma_f32_16x16x32_bf16 v[76:79], v[246:249], v[178:181], v[76:79]
	s_waitcnt vmcnt(7)
	ds_write_b128 v253, v[156:159] offset:36864
	v_mfma_f32_16x16x32_bf16 v[72:75], v[246:249], v[200:203], v[72:75]
	v_mfma_f32_16x16x32_bf16 v[68:71], v[246:249], v[204:207], v[68:71]
	v_lshl_add_u64 v[156:157], s[6:7], 0, v[166:167]
	s_nop 0
	global_load_dwordx4 v[156:159], v[156:157], off offset:256
	v_mfma_f32_16x16x32_bf16 v[64:67], v[246:249], v[208:211], v[64:67]
	ds_read_b128 v[242:245], v176 offset:13888
	s_waitcnt lgkmcnt(3)
	v_mfma_f32_16x16x32_bf16 v[60:63], v[212:215], v[178:181], v[60:63]
	v_mfma_f32_16x16x32_bf16 v[56:59], v[212:215], v[200:203], v[56:59]
	v_mfma_f32_16x16x32_bf16 v[52:55], v[212:215], v[204:207], v[52:55]
	v_mfma_f32_16x16x32_bf16 v[48:51], v[212:215], v[208:211], v[48:51]
	ds_read_b128 v[246:249], v176 offset:16192
	s_waitcnt lgkmcnt(3)
	v_mfma_f32_16x16x32_bf16 v[44:47], v[216:219], v[178:181], v[44:47]
	v_mfma_f32_16x16x32_bf16 v[40:43], v[216:219], v[200:203], v[40:43]
	v_mfma_f32_16x16x32_bf16 v[36:39], v[216:219], v[204:207], v[36:39]
	v_mfma_f32_16x16x32_bf16 v[32:35], v[216:219], v[208:211], v[32:35]
	s_waitcnt lgkmcnt(0)
	s_barrier
; DI f32x4 mfma16(bf16x8 a, bf16x8 b, f32x4 c) { return __builtin_amdgcn_mfma_f32_16x16x32_bf16(a, b, c, 0, 0, 0); }
; template <int MI, int NJ, bool SWAP, class AP, class BP>
; DI void gemm_main(f32x4 (&acc)[MI][NJ], const AP& ap, int a_kstep, const BP& bp, int b_kstep, int nk, bf16_t* smem) {
;     ...
;   for (int kt = 0; kt < nk; ++kt) {
;     const int buf = kt & 1;
;     sstore(buf ^ 1);
;     gload(kt + 2 < nk ? kt + 2 : nk - 1);
;     __builtin_amdgcn_sched_barrier(0);
;     const bf16_t* As = smem + buf * L::STAGE + (wm * 16 * MI + l15) * LDT + quad * 8;
;     const bf16_t* Bs = smem + buf * L::STAGE + L::A_ELEMS + (wn * 16 * NJ + l15) * LDT + quad * 8;
; #pragma unroll
;     for (int ks = 0; ks < 2; ++ks) {
;       if (MI * NJ >= 32 && ks == 1) asm volatile("" ::: "memory");
;       bf16x8 b[NJ];
; #pragma unroll
;       for (int j = 0; j < NJ; ++j) b[j] = *(const bf16x8*)(Bs + j * 16 * LDT + ks * 32);
; #pragma unroll
;       for (int i = 0; i < MI; ++i) {
;         const bf16x8 a = *(const bf16x8*)(As + i * 16 * LDT + ks * 32);
; #pragma unroll
;         for (int j = 0; j < NJ; ++j) acc[i][j] = SWAP ? mfma16(b[j], a, acc[i][j]) : mfma16(a, b[j], acc[i][j]);
;       }
	s_add_i32 s4, s4, 1
	s_cmp_lg_u32 s4, 16
	s_cbranch_scc0 .Lgm1_exit
	s_and_b32 s98, s4, 1
	s_mul_i32 s98, s98, 0x12000
	v_add3_u32 v176, s98, v174, v175
	v_add3_u32 v182, s98, v169, v175
	ds_read_b128 v[212:215], v176
	ds_read_b128 v[216:219], v176 offset:2304
	v_mfma_f32_16x16x32_bf16 v[28:31], v[242:245], v[178:181], v[28:31]
	v_mfma_f32_16x16x32_bf16 v[8:11], v[246:249], v[178:181], v[8:11]
	ds_read_b128 v[178:181], v182 offset:36864
	v_mfma_f32_16x16x32_bf16 v[24:27], v[242:245], v[200:203], v[24:27]
	v_mfma_f32_16x16x32_bf16 v[4:7], v[246:249], v[200:203], v[4:7]
	ds_read_b128 v[200:203], v182 offset:39168
	v_mfma_f32_16x16x32_bf16 v[20:23], v[242:245], v[204:207], v[20:23]
	v_mfma_f32_16x16x32_bf16 v[0:3], v[246:249], v[204:207], v[0:3]
	ds_read_b128 v[204:207], v182 offset:41472
	v_mfma_f32_16x16x32_bf16 v[16:19], v[242:245], v[208:211], v[16:19]
	v_mfma_f32_16x16x32_bf16 v[12:15], v[246:249], v[208:211], v[12:15]
	ds_read_b128 v[208:211], v182 offset:43776
	s_branch .Lgm1_main

; DI f32x4 mfma16(bf16x8 a, bf16x8 b, f32x4 c) { return __builtin_amdgcn_mfma_f32_16x16x32_bf16(a, b, c, 0, 0, 0); }
; template <int MI, int NJ, bool SWAP, class AP, class BP>
; DI void gemm_main(f32x4 (&acc)[MI][NJ], const AP& ap, int a_kstep, const BP& bp, int b_kstep, int nk, bf16_t* smem) {
;     ...
;   auto gload = [&](int kt) {
;     const bf16_t* ab = ap.base + (size_t)kt * a_kstep; const bf16_t* bb = bp.base + (size_t)kt * b_kstep;
; #pragma unroll
;     for (int i = 0; i < CA; ++i) ra[i] = *(const u32x4*)(ab + pa[i]);
; #pragma unroll
;     for (int i = 0; i < CB; ++i) rb[i] = *(const u32x4*)(bb + pb[i]);
;   };
;   auto sstore = [&](int buf) {
;     bf16_t* As = smem + buf * L::STAGE; bf16_t* Bs = As + L::A_ELEMS;
; #pragma unroll
;     for (int i = 0; i < CA; ++i) { const int c = tid + NTHR * i; *(u32x4*)(As + (c >> 3) * LDT + (c & 7) * 8) = oka[i] ? ra[i] : (u32x4){0u, 0u, 0u, 0u}; }
; #pragma unroll
;     for (int i = 0; i < CB; ++i) { const int c = tid + NTHR * i; *(u32x4*)(Bs + (c >> 3) * LDT + (c & 7) * 8) = rb[i]; }
;   };
;   gload(0); sstore(0); gload(nk > 1 ? 1 : 0); __syncthreads();
; #pragma unroll 1
;   for (int kt = 0; kt < nk; ++kt) {
;     const int buf = kt & 1;
;     sstore(buf ^ 1);
;     gload(kt + 2 < nk ? kt + 2 : nk - 1);
;     __builtin_amdgcn_sched_barrier(0);
;     const bf16_t* As = smem + buf * L::STAGE + (wm * 16 * MI + l15) * LDT + quad * 8;
;     const bf16_t* Bs = smem + buf * L::STAGE + L::A_ELEMS + (wn * 16 * NJ + l15) * LDT + quad * 8;
; #pragma unroll
;     for (int ks = 0; ks < 2; ++ks) {
;       if (MI * NJ >= 32 && ks == 1) asm volatile("" ::: "memory");
;       bf16x8 b[NJ];
; #pragma unroll
;       for (int j = 0; j < NJ; ++j) b[j] = *(const bf16x8*)(Bs + j * 16 * LDT + ks * 32);
; #pragma unroll
;       for (int i = 0; i < MI; ++i) {
;         const bf16x8 a = *(const bf16x8*)(As + i * 16 * LDT + ks * 32);
; #pragma unroll
;         for (int j = 0; j < NJ; ++j) acc[i][j] = SWAP ? mfma16(b[j], a, acc[i][j]) : mfma16(a, b[j], acc[i][j]);
;       }
;     }
;     __syncthreads();
;   }
.Lgm3_main:
	ds_read_b128 v[242:245], v182 offset:4608
	s_waitcnt lgkmcnt(4)
	v_mfma_f32_16x16x32_bf16 v[156:159], v[178:181], v[198:201], v[156:159]
	s_waitcnt lgkmcnt(3)
	v_mfma_f32_16x16x32_bf16 v[152:155], v[186:189], v[198:201], v[152:155]
	s_waitcnt lgkmcnt(2)
	v_mfma_f32_16x16x32_bf16 v[148:151], v[190:193], v[198:201], v[148:151]
	s_and_b32 s54, s33, 1
	s_xor_b32 s52, s54, 1
	s_cmp_eq_u32 s33, 0
	v_lshlrev_b32_e32 v250, 1, v160
	v_lshlrev_b32_e32 v251, 1, v173
	v_lshlrev_b32_e32 v252, 1, v174
	v_lshlrev_b32_e32 v253, 1, v175
	s_mul_i32 s52, s52, 0x12000
	s_cselect_b32 s55, s48, 0x180
	v_add3_u32 v250, s52, v250, v172
	v_add3_u32 v251, s52, v251, v172
	v_add3_u32 v252, s52, v252, v172
	v_add3_u32 v253, s52, v253, v172
	s_add_u32 s52, s0, s55
	s_addc_u32 s53, s1, 0
	s_waitcnt vmcnt(7)
	ds_write_b128 v250, v[112:115]
	s_waitcnt lgkmcnt(2)
	v_mfma_f32_16x16x32_bf16 v[144:147], v[194:197], v[198:201], v[144:147]
	ds_read_b128 v[246:249], v182 offset:6912
	v_mfma_f32_16x16x32_bf16 v[108:111], v[178:181], v[202:205], v[108:111]
	v_lshl_add_u64 v[112:113], s[52:53], 0, v[162:163]
	s_nop 0
	global_load_dwordx4 v[112:115], v[112:113], off
	v_mfma_f32_16x16x32_bf16 v[104:107], v[186:189], v[202:205], v[104:107]
	v_mfma_f32_16x16x32_bf16 v[100:103], v[190:193], v[202:205], v[100:103]
	v_mfma_f32_16x16x32_bf16 v[96:99], v[194:197], v[202:205], v[96:99]
	ds_read_b128 v[198:201], v182 offset:9216
	s_waitcnt lgkmcnt(3)
	v_mfma_f32_16x16x32_bf16 v[92:95], v[178:181], v[242:245], v[92:95]
	s_waitcnt vmcnt(7)
	ds_write_b128 v251, v[116:119]
	v_mfma_f32_16x16x32_bf16 v[88:91], v[186:189], v[242:245], v[88:91]
	v_mfma_f32_16x16x32_bf16 v[84:87], v[190:193], v[242:245], v[84:87]
	v_lshl_add_u64 v[116:117], s[52:53], 0, v[164:165]
	s_nop 0
	global_load_dwordx4 v[116:119], v[116:117], off
	v_mfma_f32_16x16x32_bf16 v[80:83], v[194:197], v[242:245], v[80:83]
	ds_read_b128 v[202:205], v182 offset:11520
	s_waitcnt lgkmcnt(3)
	v_mfma_f32_16x16x32_bf16 v[76:79], v[178:181], v[246:249], v[76:79]
	v_mfma_f32_16x16x32_bf16 v[72:75], v[186:189], v[246:249], v[72:75]
	v_mfma_f32_16x16x32_bf16 v[68:71], v[190:193], v[246:249], v[68:71]
	s_waitcnt vmcnt(7)
	ds_write_b128 v252, v[120:123]
	v_mfma_f32_16x16x32_bf16 v[64:67], v[194:197], v[246:249], v[64:67]
	ds_read_b128 v[242:245], v182 offset:13824
	s_waitcnt lgkmcnt(4)
	v_mfma_f32_16x16x32_bf16 v[60:63], v[178:181], v[198:201], v[60:63]
	v_lshl_add_u64 v[120:121], s[52:53], 0, v[166:167]
	s_nop 0
	global_load_dwordx4 v[120:123], v[120:121], off
	v_mfma_f32_16x16x32_bf16 v[56:59], v[186:189], v[198:201], v[56:59]
	v_mfma_f32_16x16x32_bf16 v[52:55], v[190:193], v[198:201], v[52:55]
	v_mfma_f32_16x16x32_bf16 v[48:51], v[194:197], v[198:201], v[48:51]
	ds_read_b128 v[246:249], v182 offset:16128
	s_waitcnt lgkmcnt(3)
	v_mfma_f32_16x16x32_bf16 v[44:47], v[178:181], v[202:205], v[44:47]
	s_waitcnt vmcnt(7)
	ds_write_b128 v253, v[124:127]
	v_mfma_f32_16x16x32_bf16 v[40:43], v[186:189], v[202:205], v[40:43]
	v_mfma_f32_16x16x32_bf16 v[36:39], v[190:193], v[202:205], v[36:39]
	v_lshl_add_u64 v[124:125], s[52:53], 0, v[168:169]
	s_nop 0
	global_load_dwordx4 v[124:127], v[124:125], off
	v_mfma_f32_16x16x32_bf16 v[32:35], v[194:197], v[202:205], v[32:35]
	ds_read_b128 v[198:201], v182 offset:64
	s_waitcnt lgkmcnt(3)
	v_mfma_f32_16x16x32_bf16 v[28:31], v[178:181], v[242:245], v[28:31]
	v_mfma_f32_16x16x32_bf16 v[24:27], v[186:189], v[242:245], v[24:27]
	v_mfma_f32_16x16x32_bf16 v[20:23], v[190:193], v[242:245], v[20:23]
	s_waitcnt vmcnt(7)
	ds_write_b128 v250, v[128:131] offset:36864
	v_mfma_f32_16x16x32_bf16 v[16:19], v[194:197], v[242:245], v[16:19]
	ds_read_b128 v[202:205], v182 offset:2368
	s_waitcnt lgkmcnt(4)
	v_mfma_f32_16x16x32_bf16 v[8:11], v[178:181], v[246:249], v[8:11]
	ds_read_b128 v[178:181], v183 offset:36928
	s_add_u32 s52, s2, s55
	s_addc_u32 s53, s3, 0
	v_lshl_add_u64 v[128:129], s[52:53], 0, v[162:163]
	s_nop 0
	global_load_dwordx4 v[128:131], v[128:129], off
	v_mfma_f32_16x16x32_bf16 v[4:7], v[186:189], v[246:249], v[4:7]
	ds_read_b128 v[186:189], v183 offset:39232
	v_mfma_f32_16x16x32_bf16 v[0:3], v[190:193], v[246:249], v[0:3]
	ds_read_b128 v[190:193], v183 offset:41536
	v_mfma_f32_16x16x32_bf16 v[12:15], v[194:197], v[246:249], v[12:15]
	ds_read_b128 v[194:197], v183 offset:43840
	ds_read_b128 v[242:245], v182 offset:4672
	s_waitcnt lgkmcnt(4)
	v_mfma_f32_16x16x32_bf16 v[156:159], v[178:181], v[198:201], v[156:159]
	s_waitcnt vmcnt(7)
	ds_write_b128 v251, v[132:135] offset:36864
	s_waitcnt lgkmcnt(4)
	v_mfma_f32_16x16x32_bf16 v[152:155], v[186:189], v[198:201], v[152:155]
	s_waitcnt lgkmcnt(3)
	v_mfma_f32_16x16x32_bf16 v[148:151], v[190:193], v[198:201], v[148:151]
	v_lshl_add_u64 v[132:133], s[52:53], 0, v[164:165]
	s_nop 0
	global_load_dwordx4 v[132:135], v[132:133], off
	s_waitcnt lgkmcnt(2)
	v_mfma_f32_16x16x32_bf16 v[144:147], v[194:197], v[198:201], v[144:147]
	ds_read_b128 v[246:249], v182 offset:6976
	v_mfma_f32_16x16x32_bf16 v[108:111], v[178:181], v[202:205], v[108:111]
	v_mfma_f32_16x16x32_bf16 v[104:107], v[186:189], v[202:205], v[104:107]
	v_mfma_f32_16x16x32_bf16 v[100:103], v[190:193], v[202:205], v[100:103]
	s_waitcnt vmcnt(7)
	ds_write_b128 v252, v[136:139] offset:36864
	v_mfma_f32_16x16x32_bf16 v[96:99], v[194:197], v[202:205], v[96:99]
	ds_read_b128 v[198:201], v182 offset:9280
	s_waitcnt lgkmcnt(4)
	v_mfma_f32_16x16x32_bf16 v[92:95], v[178:181], v[242:245], v[92:95]
	v_lshl_add_u64 v[136:137], s[52:53], 0, v[166:167]
	s_nop 0
	global_load_dwordx4 v[136:139], v[136:137], off
	v_mfma_f32_16x16x32_bf16 v[88:91], v[186:189], v[242:245], v[88:91]
	v_mfma_f32_16x16x32_bf16 v[84:87], v[190:193], v[242:245], v[84:87]
	v_mfma_f32_16x16x32_bf16 v[80:83], v[194:197], v[242:245], v[80:83]
	ds_read_b128 v[202:205], v182 offset:11584
	s_waitcnt lgkmcnt(3)
	v_mfma_f32_16x16x32_bf16 v[76:79], v[178:181], v[246:249], v[76:79]
	s_waitcnt vmcnt(7)
	ds_write_b128 v253, v[140:143] offset:36864
	v_mfma_f32_16x16x32_bf16 v[72:75], v[186:189], v[246:249], v[72:75]
	v_mfma_f32_16x16x32_bf16 v[68:71], v[190:193], v[246:249], v[68:71]
	v_lshl_add_u64 v[140:141], s[52:53], 0, v[168:169]
	s_nop 0
	global_load_dwordx4 v[140:143], v[140:141], off
	v_mfma_f32_16x16x32_bf16 v[64:67], v[194:197], v[246:249], v[64:67]
	ds_read_b128 v[242:245], v182 offset:13888
	s_waitcnt lgkmcnt(3)
	v_mfma_f32_16x16x32_bf16 v[60:63], v[178:181], v[198:201], v[60:63]
	v_mfma_f32_16x16x32_bf16 v[56:59], v[186:189], v[198:201], v[56:59]
	v_mfma_f32_16x16x32_bf16 v[52:55], v[190:193], v[198:201], v[52:55]
	v_mfma_f32_16x16x32_bf16 v[48:51], v[194:197], v[198:201], v[48:51]
	ds_read_b128 v[246:249], v182 offset:16192
	s_waitcnt lgkmcnt(3)
	v_mfma_f32_16x16x32_bf16 v[44:47], v[178:181], v[202:205], v[44:47]
	v_mfma_f32_16x16x32_bf16 v[40:43], v[186:189], v[202:205], v[40:43]
	v_mfma_f32_16x16x32_bf16 v[36:39], v[190:193], v[202:205], v[36:39]
	v_mfma_f32_16x16x32_bf16 v[32:35], v[194:197], v[202:205], v[32:35]
	s_waitcnt lgkmcnt(0)
	s_barrier
; DI f32x4 mfma16(bf16x8 a, bf16x8 b, f32x4 c) { return __builtin_amdgcn_mfma_f32_16x16x32_bf16(a, b, c, 0, 0, 0); }
; template <int MI, int NJ, bool SWAP, class AP, class BP>
; DI void gemm_main(f32x4 (&acc)[MI][NJ], const AP& ap, int a_kstep, const BP& bp, int b_kstep, int nk, bf16_t* smem) {
;     ...
;   for (int kt = 0; kt < nk; ++kt) {
;     const int buf = kt & 1;
;     sstore(buf ^ 1);
;     gload(kt + 2 < nk ? kt + 2 : nk - 1);
;     __builtin_amdgcn_sched_barrier(0);
;     const bf16_t* As = smem + buf * L::STAGE + (wm * 16 * MI + l15) * LDT + quad * 8;
;     const bf16_t* Bs = smem + buf * L::STAGE + L::A_ELEMS + (wn * 16 * NJ + l15) * LDT + quad * 8;
; #pragma unroll
;     for (int ks = 0; ks < 2; ++ks) {
;       if (MI * NJ >= 32 && ks == 1) asm volatile("" ::: "memory");
;       bf16x8 b[NJ];
; #pragma unroll
;       for (int j = 0; j < NJ; ++j) b[j] = *(const bf16x8*)(Bs + j * 16 * LDT + ks * 32);
; #pragma unroll
;       for (int i = 0; i < MI; ++i) {
;         const bf16x8 a = *(const bf16x8*)(As + i * 16 * LDT + ks * 32);
; #pragma unroll
;         for (int j = 0; j < NJ; ++j) acc[i][j] = SWAP ? mfma16(b[j], a, acc[i][j]) : mfma16(a, b[j], acc[i][j]);
;       }
	s_add_i32 s33, s33, 1
	s_cmp_lg_u32 s33, 4
	s_cbranch_scc0 .Lgm3_exit
	s_and_b32 s98, s33, 1
	s_mul_i32 s98, s98, 0x12000
	v_add3_u32 v183, s98, v171, v177
	v_add3_u32 v182, s98, v176, v177
	ds_read_b128 v[198:201], v182
	ds_read_b128 v[202:205], v182 offset:2304
	v_mfma_f32_16x16x32_bf16 v[28:31], v[178:181], v[242:245], v[28:31]
	v_mfma_f32_16x16x32_bf16 v[8:11], v[178:181], v[246:249], v[8:11]
	ds_read_b128 v[178:181], v183 offset:36864
	v_mfma_f32_16x16x32_bf16 v[24:27], v[186:189], v[242:245], v[24:27]
	v_mfma_f32_16x16x32_bf16 v[4:7], v[186:189], v[246:249], v[4:7]
	ds_read_b128 v[186:189], v183 offset:39168
	v_mfma_f32_16x16x32_bf16 v[20:23], v[190:193], v[242:245], v[20:23]
	v_mfma_f32_16x16x32_bf16 v[0:3], v[190:193], v[246:249], v[0:3]
	ds_read_b128 v[190:193], v183 offset:41472
	v_mfma_f32_16x16x32_bf16 v[16:19], v[194:197], v[242:245], v[16:19]
	v_mfma_f32_16x16x32_bf16 v[12:15], v[194:197], v[246:249], v[12:15]
	ds_read_b128 v[194:197], v183 offset:43776
	s_branch .Lgm3_main

; DI f32x4 mfma16(bf16x8 a, bf16x8 b, f32x4 c) { return __builtin_amdgcn_mfma_f32_16x16x32_bf16(a, b, c, 0, 0, 0); }
; template <int MI, int NJ, bool SWAP, class AP, class BP>
; DI void gemm_main(f32x4 (&acc)[MI][NJ], const AP& ap, int a_kstep, const BP& bp, int b_kstep, int nk, bf16_t* smem) {
;     ...
;   auto gload = [&](int kt) {
;     const bf16_t* ab = ap.base + (size_t)kt * a_kstep; const bf16_t* bb = bp.base + (size_t)kt * b_kstep;
; #pragma unroll
;     for (int i = 0; i < CA; ++i) ra[i] = *(const u32x4*)(ab + pa[i]);
; #pragma unroll
;     for (int i = 0; i < CB; ++i) rb[i] = *(const u32x4*)(bb + pb[i]);
;   };
;   auto sstore = [&](int buf) {
;     bf16_t* As = smem + buf * L::STAGE; bf16_t* Bs = As + L::A_ELEMS;
; #pragma unroll
;     for (int i = 0; i < CA; ++i) { const int c = tid + NTHR * i; *(u32x4*)(As + (c >> 3) * LDT + (c & 7) * 8) = oka[i] ? ra[i] : (u32x4){0u, 0u, 0u, 0u}; }
; #pragma unroll
;     for (int i = 0; i < CB; ++i) { const int c = tid + NTHR * i; *(u32x4*)(Bs + (c >> 3) * LDT + (c & 7) * 8) = rb[i]; }
;   };
;   gload(0); sstore(0); gload(nk > 1 ? 1 : 0); __syncthreads();
; #pragma unroll 1
;   for (int kt = 0; kt < nk; ++kt) {
;     const int buf = kt & 1;
;     sstore(buf ^ 1);
;     gload(kt + 2 < nk ? kt + 2 : nk - 1);
;     __builtin_amdgcn_sched_barrier(0);
;     const bf16_t* As = smem + buf * L::STAGE + (wm * 16 * MI + l15) * LDT + quad * 8;
;     const bf16_t* Bs = smem + buf * L::STAGE + L::A_ELEMS + (wn * 16 * NJ + l15) * LDT + quad * 8;
; #pragma unroll
;     for (int ks = 0; ks < 2; ++ks) {
;       if (MI * NJ >= 32 && ks == 1) asm volatile("" ::: "memory");
;       bf16x8 b[NJ];
; #pragma unroll
;       for (int j = 0; j < NJ; ++j) b[j] = *(const bf16x8*)(Bs + j * 16 * LDT + ks * 32);
; #pragma unroll
;       for (int i = 0; i < MI; ++i) {
;         const bf16x8 a = *(const bf16x8*)(As + i * 16 * LDT + ks * 32);
; #pragma unroll
;         for (int j = 0; j < NJ; ++j) acc[i][j] = SWAP ? mfma16(b[j], a, acc[i][j]) : mfma16(a, b[j], acc[i][j]);
;       }
;     }
;     __syncthreads();
;   }
.Lgm4_main:
	ds_read_b128 v[242:245], v182 offset:4608
	s_waitcnt lgkmcnt(4)
	v_mfma_f32_16x16x32_bf16 v[140:143], v[198:201], v[178:181], v[140:143]
	s_waitcnt lgkmcnt(3)
	v_mfma_f32_16x16x32_bf16 v[120:123], v[198:201], v[186:189], v[120:123]
	s_waitcnt lgkmcnt(2)
	v_mfma_f32_16x16x32_bf16 v[116:119], v[198:201], v[190:193], v[116:119]
	s_and_b32 s16, s5, 1
	s_xor_b32 s33, s16, 1
	v_lshlrev_b32_e32 v250, 1, v160
	v_lshlrev_b32_e32 v251, 1, v173
	v_lshlrev_b32_e32 v252, 1, v174
	v_lshlrev_b32_e32 v253, 1, v175
	s_mul_i32 s33, s33, 0x12000
	s_cmp_eq_u32 s5, 0
	v_add3_u32 v250, s33, v250, v172
	v_add3_u32 v251, s33, v251, v172
	v_add3_u32 v252, s33, v252, v172
	v_add3_u32 v253, s33, v253, v172
	s_cselect_b32 s33, s48, 0x180
	s_add_u32 s52, s0, s33
	s_addc_u32 s53, s1, 0
	s_waitcnt vmcnt(7)
	ds_write_b128 v250, v[124:127]
	s_waitcnt lgkmcnt(2)
	v_mfma_f32_16x16x32_bf16 v[112:115], v[198:201], v[194:197], v[112:115]
	ds_read_b128 v[246:249], v182 offset:6912
	v_mfma_f32_16x16x32_bf16 v[108:111], v[202:205], v[178:181], v[108:111]
	v_lshl_add_u64 v[124:125], s[52:53], 0, v[162:163]
	s_nop 0
	global_load_dwordx4 v[124:127], v[124:125], off
	v_mfma_f32_16x16x32_bf16 v[104:107], v[202:205], v[186:189], v[104:107]
	v_mfma_f32_16x16x32_bf16 v[100:103], v[202:205], v[190:193], v[100:103]
	v_mfma_f32_16x16x32_bf16 v[96:99], v[202:205], v[194:197], v[96:99]
	ds_read_b128 v[198:201], v182 offset:9216
	s_waitcnt lgkmcnt(3)
	v_mfma_f32_16x16x32_bf16 v[92:95], v[242:245], v[178:181], v[92:95]
	s_waitcnt vmcnt(7)
	ds_write_b128 v251, v[128:131]
	v_mfma_f32_16x16x32_bf16 v[88:91], v[242:245], v[186:189], v[88:91]
	v_mfma_f32_16x16x32_bf16 v[84:87], v[242:245], v[190:193], v[84:87]
	v_lshl_add_u64 v[128:129], s[52:53], 0, v[164:165]
	s_nop 0
	global_load_dwordx4 v[128:131], v[128:129], off
	v_mfma_f32_16x16x32_bf16 v[80:83], v[242:245], v[194:197], v[80:83]
	ds_read_b128 v[202:205], v182 offset:11520
	s_waitcnt lgkmcnt(3)
	v_mfma_f32_16x16x32_bf16 v[76:79], v[246:249], v[178:181], v[76:79]
	v_mfma_f32_16x16x32_bf16 v[72:75], v[246:249], v[186:189], v[72:75]
	v_mfma_f32_16x16x32_bf16 v[68:71], v[246:249], v[190:193], v[68:71]
	s_waitcnt vmcnt(7)
	ds_write_b128 v252, v[132:135]
	v_mfma_f32_16x16x32_bf16 v[64:67], v[246:249], v[194:197], v[64:67]
	ds_read_b128 v[242:245], v182 offset:13824
	s_waitcnt lgkmcnt(4)
	v_mfma_f32_16x16x32_bf16 v[60:63], v[198:201], v[178:181], v[60:63]
	v_lshl_add_u64 v[132:133], s[52:53], 0, v[166:167]
	s_nop 0
	global_load_dwordx4 v[132:135], v[132:133], off
	v_mfma_f32_16x16x32_bf16 v[56:59], v[198:201], v[186:189], v[56:59]
	v_mfma_f32_16x16x32_bf16 v[52:55], v[198:201], v[190:193], v[52:55]
	v_mfma_f32_16x16x32_bf16 v[48:51], v[198:201], v[194:197], v[48:51]
	ds_read_b128 v[246:249], v182 offset:16128
	s_waitcnt lgkmcnt(3)
	v_mfma_f32_16x16x32_bf16 v[44:47], v[202:205], v[178:181], v[44:47]
	s_waitcnt vmcnt(7)
	ds_write_b128 v253, v[136:139]
	v_mfma_f32_16x16x32_bf16 v[40:43], v[202:205], v[186:189], v[40:43]
	v_mfma_f32_16x16x32_bf16 v[36:39], v[202:205], v[190:193], v[36:39]
	v_lshl_add_u64 v[136:137], s[52:53], 0, v[168:169]
	s_nop 0
	global_load_dwordx4 v[136:139], v[136:137], off
	v_mfma_f32_16x16x32_bf16 v[32:35], v[202:205], v[194:197], v[32:35]
	ds_read_b128 v[198:201], v182 offset:64
	s_waitcnt lgkmcnt(3)
	v_mfma_f32_16x16x32_bf16 v[28:31], v[242:245], v[178:181], v[28:31]
	v_mfma_f32_16x16x32_bf16 v[24:27], v[242:245], v[186:189], v[24:27]
	v_mfma_f32_16x16x32_bf16 v[20:23], v[242:245], v[190:193], v[20:23]
	s_waitcnt vmcnt(7)
	ds_write_b128 v250, v[144:147] offset:36864
	v_mfma_f32_16x16x32_bf16 v[16:19], v[242:245], v[194:197], v[16:19]
	ds_read_b128 v[202:205], v182 offset:2368
	s_waitcnt lgkmcnt(4)
	v_mfma_f32_16x16x32_bf16 v[8:11], v[246:249], v[178:181], v[8:11]
	ds_read_b128 v[178:181], v183 offset:36928
	s_add_u32 s52, s2, s33
	s_addc_u32 s53, s3, 0
	v_lshl_add_u64 v[144:145], s[52:53], 0, v[162:163]
	s_nop 0
	global_load_dwordx4 v[144:147], v[144:145], off
	v_mfma_f32_16x16x32_bf16 v[4:7], v[246:249], v[186:189], v[4:7]
	ds_read_b128 v[186:189], v183 offset:39232
	v_mfma_f32_16x16x32_bf16 v[0:3], v[246:249], v[190:193], v[0:3]
	ds_read_b128 v[190:193], v183 offset:41536
	v_mfma_f32_16x16x32_bf16 v[12:15], v[246:249], v[194:197], v[12:15]
	ds_read_b128 v[194:197], v183 offset:43840
	ds_read_b128 v[242:245], v182 offset:4672
	s_waitcnt lgkmcnt(4)
	v_mfma_f32_16x16x32_bf16 v[140:143], v[198:201], v[178:181], v[140:143]
	s_waitcnt vmcnt(7)
	ds_write_b128 v251, v[148:151] offset:36864
	s_waitcnt lgkmcnt(4)
	v_mfma_f32_16x16x32_bf16 v[120:123], v[198:201], v[186:189], v[120:123]
	s_waitcnt lgkmcnt(3)
	v_mfma_f32_16x16x32_bf16 v[116:119], v[198:201], v[190:193], v[116:119]
	v_lshl_add_u64 v[148:149], s[52:53], 0, v[164:165]
	s_nop 0
	global_load_dwordx4 v[148:151], v[148:149], off
	s_waitcnt lgkmcnt(2)
	v_mfma_f32_16x16x32_bf16 v[112:115], v[198:201], v[194:197], v[112:115]
	ds_read_b128 v[246:249], v182 offset:6976
	v_mfma_f32_16x16x32_bf16 v[108:111], v[202:205], v[178:181], v[108:111]
	v_mfma_f32_16x16x32_bf16 v[104:107], v[202:205], v[186:189], v[104:107]
	v_mfma_f32_16x16x32_bf16 v[100:103], v[202:205], v[190:193], v[100:103]
	s_waitcnt vmcnt(7)
	ds_write_b128 v252, v[152:155] offset:36864
	v_mfma_f32_16x16x32_bf16 v[96:99], v[202:205], v[194:197], v[96:99]
	ds_read_b128 v[198:201], v182 offset:9280
	s_waitcnt lgkmcnt(4)
	v_mfma_f32_16x16x32_bf16 v[92:95], v[242:245], v[178:181], v[92:95]
	v_lshl_add_u64 v[152:153], s[52:53], 0, v[166:167]
	s_nop 0
	global_load_dwordx4 v[152:155], v[152:153], off
	v_mfma_f32_16x16x32_bf16 v[88:91], v[242:245], v[186:189], v[88:91]
	v_mfma_f32_16x16x32_bf16 v[84:87], v[242:245], v[190:193], v[84:87]
	v_mfma_f32_16x16x32_bf16 v[80:83], v[242:245], v[194:197], v[80:83]
	ds_read_b128 v[202:205], v182 offset:11584
	s_waitcnt lgkmcnt(3)
	v_mfma_f32_16x16x32_bf16 v[76:79], v[246:249], v[178:181], v[76:79]
	s_waitcnt vmcnt(7)
	ds_write_b128 v253, v[156:159] offset:36864
	v_mfma_f32_16x16x32_bf16 v[72:75], v[246:249], v[186:189], v[72:75]
	v_mfma_f32_16x16x32_bf16 v[68:71], v[246:249], v[190:193], v[68:71]
	v_lshl_add_u64 v[156:157], s[52:53], 0, v[168:169]
	s_nop 0
	global_load_dwordx4 v[156:159], v[156:157], off
	v_mfma_f32_16x16x32_bf16 v[64:67], v[246:249], v[194:197], v[64:67]
	ds_read_b128 v[242:245], v182 offset:13888
	s_waitcnt lgkmcnt(3)
	v_mfma_f32_16x16x32_bf16 v[60:63], v[198:201], v[178:181], v[60:63]
	v_mfma_f32_16x16x32_bf16 v[56:59], v[198:201], v[186:189], v[56:59]
	v_mfma_f32_16x16x32_bf16 v[52:55], v[198:201], v[190:193], v[52:55]
	v_mfma_f32_16x16x32_bf16 v[48:51], v[198:201], v[194:197], v[48:51]
	ds_read_b128 v[246:249], v182 offset:16192
	s_waitcnt lgkmcnt(3)
	v_mfma_f32_16x16x32_bf16 v[44:47], v[202:205], v[178:181], v[44:47]
	v_mfma_f32_16x16x32_bf16 v[40:43], v[202:205], v[186:189], v[40:43]
	v_mfma_f32_16x16x32_bf16 v[36:39], v[202:205], v[190:193], v[36:39]
	v_mfma_f32_16x16x32_bf16 v[32:35], v[202:205], v[194:197], v[32:35]
	s_waitcnt lgkmcnt(0)
	s_barrier
; DI f32x4 mfma16(bf16x8 a, bf16x8 b, f32x4 c) { return __builtin_amdgcn_mfma_f32_16x16x32_bf16(a, b, c, 0, 0, 0); }
; template <int MI, int NJ, bool SWAP, class AP, class BP>
; DI void gemm_main(f32x4 (&acc)[MI][NJ], const AP& ap, int a_kstep, const BP& bp, int b_kstep, int nk, bf16_t* smem) {
;     ...
;   for (int kt = 0; kt < nk; ++kt) {
;     const int buf = kt & 1;
;     sstore(buf ^ 1);
;     gload(kt + 2 < nk ? kt + 2 : nk - 1);
;     __builtin_amdgcn_sched_barrier(0);
;     const bf16_t* As = smem + buf * L::STAGE + (wm * 16 * MI + l15) * LDT + quad * 8;
;     const bf16_t* Bs = smem + buf * L::STAGE + L::A_ELEMS + (wn * 16 * NJ + l15) * LDT + quad * 8;
; #pragma unroll
;     for (int ks = 0; ks < 2; ++ks) {
;       if (MI * NJ >= 32 && ks == 1) asm volatile("" ::: "memory");
;       bf16x8 b[NJ];
; #pragma unroll
;       for (int j = 0; j < NJ; ++j) b[j] = *(const bf16x8*)(Bs + j * 16 * LDT + ks * 32);
; #pragma unroll
;       for (int i = 0; i < MI; ++i) {
;         const bf16x8 a = *(const bf16x8*)(As + i * 16 * LDT + ks * 32);
; #pragma unroll
;         for (int j = 0; j < NJ; ++j) acc[i][j] = SWAP ? mfma16(b[j], a, acc[i][j]) : mfma16(a, b[j], acc[i][j]);
;       }
	s_add_i32 s5, s5, 1
	s_cmp_lg_u32 s5, 4
	s_cbranch_scc0 .Lgm4_exit
	s_and_b32 s98, s5, 1
	s_mul_i32 s98, s98, 0x12000
	v_add3_u32 v182, s98, v176, v177
	v_add3_u32 v183, s98, v171, v177
	ds_read_b128 v[198:201], v182
	ds_read_b128 v[202:205], v182 offset:2304
	v_mfma_f32_16x16x32_bf16 v[28:31], v[242:245], v[178:181], v[28:31]
	v_mfma_f32_16x16x32_bf16 v[8:11], v[246:249], v[178:181], v[8:11]
	ds_read_b128 v[178:181], v183 offset:36864
	v_mfma_f32_16x16x32_bf16 v[24:27], v[242:245], v[186:189], v[24:27]
	v_mfma_f32_16x16x32_bf16 v[4:7], v[246:249], v[186:189], v[4:7]
	ds_read_b128 v[186:189], v183 offset:39168
	v_mfma_f32_16x16x32_bf16 v[20:23], v[242:245], v[190:193], v[20:23]
	v_mfma_f32_16x16x32_bf16 v[0:3], v[246:249], v[190:193], v[0:3]
	ds_read_b128 v[190:193], v183 offset:41472
	v_mfma_f32_16x16x32_bf16 v[16:19], v[242:245], v[194:197], v[16:19]
	v_mfma_f32_16x16x32_bf16 v[12:15], v[246:249], v[194:197], v[12:15]
	ds_read_b128 v[194:197], v183 offset:43776
	s_branch .Lgm4_main

; DI f32x4 mfma16(bf16x8 a, bf16x8 b, f32x4 c) { return __builtin_amdgcn_mfma_f32_16x16x32_bf16(a, b, c, 0, 0, 0); }
; template <int MI, int NJ, bool SWAP, class AP, class BP>
; DI void gemm_main(f32x4 (&acc)[MI][NJ], const AP& ap, int a_kstep, const BP& bp, int b_kstep, int nk, bf16_t* smem) {
;     ...
;   auto gload = [&](int kt) {
;     const bf16_t* ab = ap.base + (size_t)kt * a_kstep; const bf16_t* bb = bp.base + (size_t)kt * b_kstep;
; #pragma unroll
;     for (int i = 0; i < CA; ++i) ra[i] = *(const u32x4*)(ab + pa[i]);
; #pragma unroll
;     for (int i = 0; i < CB; ++i) rb[i] = *(const u32x4*)(bb + pb[i]);
;   };
;   auto sstore = [&](int buf) {
;     bf16_t* As = smem + buf * L::STAGE; bf16_t* Bs = As + L::A_ELEMS;
; #pragma unroll
;     for (int i = 0; i < CA; ++i) { const int c = tid + NTHR * i; *(u32x4*)(As + (c >> 3) * LDT + (c & 7) * 8) = oka[i] ? ra[i] : (u32x4){0u, 0u, 0u, 0u}; }
; #pragma unroll
;     for (int i = 0; i < CB; ++i) { const int c = tid + NTHR * i; *(u32x4*)(Bs + (c >> 3) * LDT + (c & 7) * 8) = rb[i]; }
;   };
;   gload(0); sstore(0); gload(nk > 1 ? 1 : 0); __syncthreads();
; #pragma unroll 1
;   for (int kt = 0; kt < nk; ++kt) {
;     const int buf = kt & 1;
;     sstore(buf ^ 1);
;     gload(kt + 2 < nk ? kt + 2 : nk - 1);
;     __builtin_amdgcn_sched_barrier(0);
;     const bf16_t* As = smem + buf * L::STAGE + (wm * 16 * MI + l15) * LDT + quad * 8;
;     const bf16_t* Bs = smem + buf * L::STAGE + L::A_ELEMS + (wn * 16 * NJ + l15) * LDT + quad * 8;
; #pragma unroll
;     for (int ks = 0; ks < 2; ++ks) {
;       if (MI * NJ >= 32 && ks == 1) asm volatile("" ::: "memory");
;       bf16x8 b[NJ];
; #pragma unroll
;       for (int j = 0; j < NJ; ++j) b[j] = *(const bf16x8*)(Bs + j * 16 * LDT + ks * 32);
; #pragma unroll
;       for (int i = 0; i < MI; ++i) {
;         const bf16x8 a = *(const bf16x8*)(As + i * 16 * LDT + ks * 32);
; #pragma unroll
;         for (int j = 0; j < NJ; ++j) acc[i][j] = SWAP ? mfma16(b[j], a, acc[i][j]) : mfma16(a, b[j], acc[i][j]);
;       }
;     }
;     __syncthreads();
;   }
.Lgm5_main:
	ds_read_b128 v[242:245], v177 offset:4608
	s_waitcnt lgkmcnt(4)
	v_mfma_f32_16x16x32_bf16 v[156:159], v[178:181], v[194:197], v[156:159]
	s_waitcnt lgkmcnt(3)
	v_mfma_f32_16x16x32_bf16 v[152:155], v[182:185], v[194:197], v[152:155]
	s_waitcnt lgkmcnt(2)
	v_mfma_f32_16x16x32_bf16 v[148:151], v[186:189], v[194:197], v[148:151]
	s_and_b32 s15, s1, 1
	s_min_u32 s16, s1, 13
	s_xor_b32 s17, s15, 1
	s_lshl_b32 s26, s16, 7
	s_mul_i32 s17, s17, 0x12000
	s_add_u32 s16, s2, s26
	v_add3_u32 v250, s17, v172, v170
	v_add3_u32 v251, s17, v174, v170
	v_add3_u32 v252, s17, v175, v170
	v_add3_u32 v253, s17, v176, v170
	s_addc_u32 s17, s3, 0
	s_waitcnt vmcnt(7)
	ds_write_b128 v250, v[112:115]
	s_waitcnt lgkmcnt(2)
	v_mfma_f32_16x16x32_bf16 v[128:131], v[190:193], v[194:197], v[128:131]
	ds_read_b128 v[246:249], v177 offset:6912
	v_mfma_f32_16x16x32_bf16 v[108:111], v[178:181], v[198:201], v[108:111]
	v_lshl_add_u64 v[112:113], s[16:17], 0, v[162:163]
	s_nop 0
	global_load_dwordx4 v[112:115], v[112:113], off offset:256
	v_mfma_f32_16x16x32_bf16 v[104:107], v[182:185], v[198:201], v[104:107]
	v_mfma_f32_16x16x32_bf16 v[100:103], v[186:189], v[198:201], v[100:103]
	v_mfma_f32_16x16x32_bf16 v[96:99], v[190:193], v[198:201], v[96:99]
	ds_read_b128 v[194:197], v177 offset:9216
	s_waitcnt lgkmcnt(3)
	v_mfma_f32_16x16x32_bf16 v[92:95], v[178:181], v[242:245], v[92:95]
	s_waitcnt vmcnt(7)
	ds_write_b128 v251, v[116:119]
	v_mfma_f32_16x16x32_bf16 v[88:91], v[182:185], v[242:245], v[88:91]
	v_mfma_f32_16x16x32_bf16 v[84:87], v[186:189], v[242:245], v[84:87]
	v_lshl_add_u64 v[116:117], s[16:17], 0, v[164:165]
	s_nop 0
	global_load_dwordx4 v[116:119], v[116:117], off offset:256
	v_mfma_f32_16x16x32_bf16 v[80:83], v[190:193], v[242:245], v[80:83]
	ds_read_b128 v[198:201], v177 offset:11520
	s_waitcnt lgkmcnt(3)
	v_mfma_f32_16x16x32_bf16 v[76:79], v[178:181], v[246:249], v[76:79]
	v_mfma_f32_16x16x32_bf16 v[72:75], v[182:185], v[246:249], v[72:75]
	v_mfma_f32_16x16x32_bf16 v[68:71], v[186:189], v[246:249], v[68:71]
	s_waitcnt vmcnt(7)
	ds_write_b128 v252, v[120:123]
	v_mfma_f32_16x16x32_bf16 v[64:67], v[190:193], v[246:249], v[64:67]
	ds_read_b128 v[242:245], v177 offset:13824
	s_waitcnt lgkmcnt(4)
	v_mfma_f32_16x16x32_bf16 v[60:63], v[178:181], v[194:197], v[60:63]
	v_lshl_add_u64 v[120:121], s[16:17], 0, v[166:167]
	s_nop 0
	global_load_dwordx4 v[120:123], v[120:121], off offset:256
	v_mfma_f32_16x16x32_bf16 v[56:59], v[182:185], v[194:197], v[56:59]
	v_mfma_f32_16x16x32_bf16 v[52:55], v[186:189], v[194:197], v[52:55]
	v_mfma_f32_16x16x32_bf16 v[48:51], v[190:193], v[194:197], v[48:51]
	ds_read_b128 v[246:249], v177 offset:16128
	s_waitcnt lgkmcnt(3)
	v_mfma_f32_16x16x32_bf16 v[44:47], v[178:181], v[198:201], v[44:47]
	s_waitcnt vmcnt(7)
	ds_write_b128 v253, v[124:127]
	v_mfma_f32_16x16x32_bf16 v[40:43], v[182:185], v[198:201], v[40:43]
	v_mfma_f32_16x16x32_bf16 v[36:39], v[186:189], v[198:201], v[36:39]
	v_lshl_add_u64 v[124:125], s[16:17], 0, v[168:169]
	s_nop 0
	global_load_dwordx4 v[124:127], v[124:125], off offset:256
	v_mfma_f32_16x16x32_bf16 v[32:35], v[190:193], v[198:201], v[32:35]
	ds_read_b128 v[194:197], v177 offset:64
	s_waitcnt lgkmcnt(3)
	v_mfma_f32_16x16x32_bf16 v[28:31], v[178:181], v[242:245], v[28:31]
	v_mfma_f32_16x16x32_bf16 v[24:27], v[182:185], v[242:245], v[24:27]
	v_mfma_f32_16x16x32_bf16 v[20:23], v[186:189], v[242:245], v[20:23]
	s_waitcnt vmcnt(7)
	ds_write_b128 v250, v[132:135] offset:36864
	v_mfma_f32_16x16x32_bf16 v[16:19], v[190:193], v[242:245], v[16:19]
	ds_read_b128 v[198:201], v177 offset:2368
	s_waitcnt lgkmcnt(4)
	v_mfma_f32_16x16x32_bf16 v[8:11], v[178:181], v[246:249], v[8:11]
	ds_read_b128 v[178:181], v202 offset:36928
	s_add_u32 s16, s12, s26
	s_addc_u32 s17, s13, 0
	v_lshl_add_u64 v[132:133], s[16:17], 0, v[162:163]
	s_nop 0
	global_load_dwordx4 v[132:135], v[132:133], off offset:256
	v_mfma_f32_16x16x32_bf16 v[4:7], v[182:185], v[246:249], v[4:7]
	ds_read_b128 v[182:185], v202 offset:39232
	v_mfma_f32_16x16x32_bf16 v[0:3], v[186:189], v[246:249], v[0:3]
	ds_read_b128 v[186:189], v202 offset:41536
	v_mfma_f32_16x16x32_bf16 v[12:15], v[190:193], v[246:249], v[12:15]
	ds_read_b128 v[190:193], v202 offset:43840
	ds_read_b128 v[242:245], v177 offset:4672
	s_waitcnt lgkmcnt(4)
	v_mfma_f32_16x16x32_bf16 v[156:159], v[178:181], v[194:197], v[156:159]
	s_waitcnt vmcnt(7)
	ds_write_b128 v251, v[136:139] offset:36864
	s_waitcnt lgkmcnt(4)
	v_mfma_f32_16x16x32_bf16 v[152:155], v[182:185], v[194:197], v[152:155]
	s_waitcnt lgkmcnt(3)
	v_mfma_f32_16x16x32_bf16 v[148:151], v[186:189], v[194:197], v[148:151]
	v_lshl_add_u64 v[136:137], s[16:17], 0, v[164:165]
	s_nop 0
	global_load_dwordx4 v[136:139], v[136:137], off offset:256
	s_waitcnt lgkmcnt(2)
	v_mfma_f32_16x16x32_bf16 v[128:131], v[190:193], v[194:197], v[128:131]
	ds_read_b128 v[246:249], v177 offset:6976
	v_mfma_f32_16x16x32_bf16 v[108:111], v[178:181], v[198:201], v[108:111]
	v_mfma_f32_16x16x32_bf16 v[104:107], v[182:185], v[198:201], v[104:107]
	v_mfma_f32_16x16x32_bf16 v[100:103], v[186:189], v[198:201], v[100:103]
	s_waitcnt vmcnt(7)
	ds_write_b128 v252, v[140:143] offset:36864
	v_mfma_f32_16x16x32_bf16 v[96:99], v[190:193], v[198:201], v[96:99]
	ds_read_b128 v[194:197], v177 offset:9280
	s_waitcnt lgkmcnt(4)
	v_mfma_f32_16x16x32_bf16 v[92:95], v[178:181], v[242:245], v[92:95]
	v_lshl_add_u64 v[140:141], s[16:17], 0, v[166:167]
	s_nop 0
	global_load_dwordx4 v[140:143], v[140:141], off offset:256
	v_mfma_f32_16x16x32_bf16 v[88:91], v[182:185], v[242:245], v[88:91]
	v_mfma_f32_16x16x32_bf16 v[84:87], v[186:189], v[242:245], v[84:87]
	v_mfma_f32_16x16x32_bf16 v[80:83], v[190:193], v[242:245], v[80:83]
	ds_read_b128 v[198:201], v177 offset:11584
	s_waitcnt lgkmcnt(3)
	v_mfma_f32_16x16x32_bf16 v[76:79], v[178:181], v[246:249], v[76:79]
	s_waitcnt vmcnt(7)
	ds_write_b128 v253, v[144:147] offset:36864
	v_mfma_f32_16x16x32_bf16 v[72:75], v[182:185], v[246:249], v[72:75]
	v_mfma_f32_16x16x32_bf16 v[68:71], v[186:189], v[246:249], v[68:71]
	v_lshl_add_u64 v[144:145], s[16:17], 0, v[168:169]
	s_nop 0
	global_load_dwordx4 v[144:147], v[144:145], off offset:256
	v_mfma_f32_16x16x32_bf16 v[64:67], v[190:193], v[246:249], v[64:67]
	ds_read_b128 v[242:245], v177 offset:13888
	s_waitcnt lgkmcnt(3)
	v_mfma_f32_16x16x32_bf16 v[60:63], v[178:181], v[194:197], v[60:63]
	v_mfma_f32_16x16x32_bf16 v[56:59], v[182:185], v[194:197], v[56:59]
	v_mfma_f32_16x16x32_bf16 v[52:55], v[186:189], v[194:197], v[52:55]
	v_mfma_f32_16x16x32_bf16 v[48:51], v[190:193], v[194:197], v[48:51]
	ds_read_b128 v[246:249], v177 offset:16192
	s_waitcnt lgkmcnt(3)
	v_mfma_f32_16x16x32_bf16 v[44:47], v[178:181], v[198:201], v[44:47]
	v_mfma_f32_16x16x32_bf16 v[40:43], v[182:185], v[198:201], v[40:43]
	v_mfma_f32_16x16x32_bf16 v[36:39], v[186:189], v[198:201], v[36:39]
	v_mfma_f32_16x16x32_bf16 v[32:35], v[190:193], v[198:201], v[32:35]
	s_waitcnt lgkmcnt(0)
	s_barrier
; DI f32x4 mfma16(bf16x8 a, bf16x8 b, f32x4 c) { return __builtin_amdgcn_mfma_f32_16x16x32_bf16(a, b, c, 0, 0, 0); }
; template <int MI, int NJ, bool SWAP, class AP, class BP>
; DI void gemm_main(f32x4 (&acc)[MI][NJ], const AP& ap, int a_kstep, const BP& bp, int b_kstep, int nk, bf16_t* smem) {
;     ...
;   for (int kt = 0; kt < nk; ++kt) {
;     const int buf = kt & 1;
;     sstore(buf ^ 1);
;     gload(kt + 2 < nk ? kt + 2 : nk - 1);
;     __builtin_amdgcn_sched_barrier(0);
;     const bf16_t* As = smem + buf * L::STAGE + (wm * 16 * MI + l15) * LDT + quad * 8;
;     const bf16_t* Bs = smem + buf * L::STAGE + L::A_ELEMS + (wn * 16 * NJ + l15) * LDT + quad * 8;
; #pragma unroll
;     for (int ks = 0; ks < 2; ++ks) {
;       if (MI * NJ >= 32 && ks == 1) asm volatile("" ::: "memory");
;       bf16x8 b[NJ];
; #pragma unroll
;       for (int j = 0; j < NJ; ++j) b[j] = *(const bf16x8*)(Bs + j * 16 * LDT + ks * 32);
; #pragma unroll
;       for (int i = 0; i < MI; ++i) {
;         const bf16x8 a = *(const bf16x8*)(As + i * 16 * LDT + ks * 32);
; #pragma unroll
;         for (int j = 0; j < NJ; ++j) acc[i][j] = SWAP ? mfma16(b[j], a, acc[i][j]) : mfma16(a, b[j], acc[i][j]);
;       }
	s_add_i32 s1, s1, 1
	s_cmp_lg_u32 s1, 16
	s_cbranch_scc0 .Lgm5_exit
	s_and_b32 s98, s1, 1
	s_mul_i32 s98, s98, 0x12000
	v_add3_u32 v202, s98, v160, v173
	v_add3_u32 v177, s98, v171, v173
	ds_read_b128 v[194:197], v177
	ds_read_b128 v[198:201], v177 offset:2304
	v_mfma_f32_16x16x32_bf16 v[28:31], v[178:181], v[242:245], v[28:31]
	v_mfma_f32_16x16x32_bf16 v[8:11], v[178:181], v[246:249], v[8:11]
	ds_read_b128 v[178:181], v202 offset:36864
	v_mfma_f32_16x16x32_bf16 v[24:27], v[182:185], v[242:245], v[24:27]
	v_mfma_f32_16x16x32_bf16 v[4:7], v[182:185], v[246:249], v[4:7]
	ds_read_b128 v[182:185], v202 offset:39168
	v_mfma_f32_16x16x32_bf16 v[20:23], v[186:189], v[242:245], v[20:23]
	v_mfma_f32_16x16x32_bf16 v[0:3], v[186:189], v[246:249], v[0:3]
	ds_read_b128 v[186:189], v202 offset:41472
	v_mfma_f32_16x16x32_bf16 v[16:19], v[190:193], v[242:245], v[16:19]
	v_mfma_f32_16x16x32_bf16 v[12:15], v[190:193], v[246:249], v[12:15]
	ds_read_b128 v[190:193], v202 offset:43776
	s_branch .Lgm5_main

; DI f32x4 mfma16(bf16x8 a, bf16x8 b, f32x4 c) { return __builtin_amdgcn_mfma_f32_16x16x32_bf16(a, b, c, 0, 0, 0); }
; template <int MI, int NJ, bool SWAP, class AP, class BP>
; DI void gemm_main(f32x4 (&acc)[MI][NJ], const AP& ap, int a_kstep, const BP& bp, int b_kstep, int nk, bf16_t* smem) {
;     ...
;   auto gload = [&](int kt) {
;     const bf16_t* ab = ap.base + (size_t)kt * a_kstep; const bf16_t* bb = bp.base + (size_t)kt * b_kstep;
; #pragma unroll
;     for (int i = 0; i < CA; ++i) ra[i] = *(const u32x4*)(ab + pa[i]);
; #pragma unroll
;     for (int i = 0; i < CB; ++i) rb[i] = *(const u32x4*)(bb + pb[i]);
;   };
;   auto sstore = [&](int buf) {
;     bf16_t* As = smem + buf * L::STAGE; bf16_t* Bs = As + L::A_ELEMS;
; #pragma unroll
;     for (int i = 0; i < CA; ++i) { const int c = tid + NTHR * i; *(u32x4*)(As + (c >> 3) * LDT + (c & 7) * 8) = oka[i] ? ra[i] : (u32x4){0u, 0u, 0u, 0u}; }
; #pragma unroll
;     for (int i = 0; i < CB; ++i) { const int c = tid + NTHR * i; *(u32x4*)(Bs + (c >> 3) * LDT + (c & 7) * 8) = rb[i]; }
;   };
;   gload(0); sstore(0); gload(nk > 1 ? 1 : 0); __syncthreads();
; #pragma unroll 1
;   for (int kt = 0; kt < nk; ++kt) {
;     const int buf = kt & 1;
;     sstore(buf ^ 1);
;     gload(kt + 2 < nk ? kt + 2 : nk - 1);
;     __builtin_amdgcn_sched_barrier(0);
;     const bf16_t* As = smem + buf * L::STAGE + (wm * 16 * MI + l15) * LDT + quad * 8;
;     const bf16_t* Bs = smem + buf * L::STAGE + L::A_ELEMS + (wn * 16 * NJ + l15) * LDT + quad * 8;
; #pragma unroll
;     for (int ks = 0; ks < 2; ++ks) {
;       if (MI * NJ >= 32 && ks == 1) asm volatile("" ::: "memory");
;       bf16x8 b[NJ];
; #pragma unroll
;       for (int j = 0; j < NJ; ++j) b[j] = *(const bf16x8*)(Bs + j * 16 * LDT + ks * 32);
; #pragma unroll
;       for (int i = 0; i < MI; ++i) {
;         const bf16x8 a = *(const bf16x8*)(As + i * 16 * LDT + ks * 32);
; #pragma unroll
;         for (int j = 0; j < NJ; ++j) acc[i][j] = SWAP ? mfma16(b[j], a, acc[i][j]) : mfma16(a, b[j], acc[i][j]);
;       }
;     }
;     __syncthreads();
;   }
.Lgm7_main:
	ds_read_b128 v[242:245], v177 offset:4608
	s_waitcnt lgkmcnt(4)
	v_mfma_f32_16x16x32_bf16 v[156:159], v[178:181], v[194:197], v[156:159]
	s_waitcnt lgkmcnt(3)
	v_mfma_f32_16x16x32_bf16 v[152:155], v[182:185], v[194:197], v[152:155]
	s_waitcnt lgkmcnt(2)
	v_mfma_f32_16x16x32_bf16 v[148:151], v[186:189], v[194:197], v[148:151]
	s_and_b32 s24, s21, 1
	s_min_u32 s22, s21, 41
	s_xor_b32 s23, s24, 1
	s_lshl_b32 s25, s22, 7
	s_mul_i32 s23, s23, 0x12000
	s_add_u32 s22, s6, s25
	v_add3_u32 v250, s23, v172, v170
	v_add3_u32 v251, s23, v173, v170
	v_add3_u32 v252, s23, v174, v170
	v_add3_u32 v253, s23, v175, v170
	s_addc_u32 s23, s7, 0
	s_waitcnt vmcnt(7)
	ds_write_b128 v250, v[112:115]
	s_waitcnt lgkmcnt(2)
	v_mfma_f32_16x16x32_bf16 v[144:147], v[190:193], v[194:197], v[144:147]
	ds_read_b128 v[246:249], v177 offset:6912
	v_mfma_f32_16x16x32_bf16 v[108:111], v[178:181], v[198:201], v[108:111]
	v_lshl_add_u64 v[112:113], s[22:23], 0, v[162:163]
	s_nop 0
	global_load_dwordx4 v[112:115], v[112:113], off offset:256
	v_mfma_f32_16x16x32_bf16 v[104:107], v[182:185], v[198:201], v[104:107]
	v_mfma_f32_16x16x32_bf16 v[100:103], v[186:189], v[198:201], v[100:103]
	v_mfma_f32_16x16x32_bf16 v[96:99], v[190:193], v[198:201], v[96:99]
	ds_read_b128 v[194:197], v177 offset:9216
	s_waitcnt lgkmcnt(3)
	v_mfma_f32_16x16x32_bf16 v[92:95], v[178:181], v[242:245], v[92:95]
	s_waitcnt vmcnt(7)
	ds_write_b128 v251, v[116:119]
	v_mfma_f32_16x16x32_bf16 v[88:91], v[182:185], v[242:245], v[88:91]
	v_mfma_f32_16x16x32_bf16 v[84:87], v[186:189], v[242:245], v[84:87]
	v_lshl_add_u64 v[116:117], s[22:23], 0, v[164:165]
	s_nop 0
	global_load_dwordx4 v[116:119], v[116:117], off offset:256
	v_mfma_f32_16x16x32_bf16 v[80:83], v[190:193], v[242:245], v[80:83]
	ds_read_b128 v[198:201], v177 offset:11520
	s_waitcnt lgkmcnt(3)
	v_mfma_f32_16x16x32_bf16 v[76:79], v[178:181], v[246:249], v[76:79]
	v_mfma_f32_16x16x32_bf16 v[72:75], v[182:185], v[246:249], v[72:75]
	v_mfma_f32_16x16x32_bf16 v[68:71], v[186:189], v[246:249], v[68:71]
	s_waitcnt vmcnt(7)
	ds_write_b128 v252, v[120:123]
	v_mfma_f32_16x16x32_bf16 v[64:67], v[190:193], v[246:249], v[64:67]
	ds_read_b128 v[242:245], v177 offset:13824
	s_waitcnt lgkmcnt(4)
	v_mfma_f32_16x16x32_bf16 v[60:63], v[178:181], v[194:197], v[60:63]
	v_lshl_add_u64 v[120:121], s[22:23], 0, v[166:167]
	s_nop 0
	global_load_dwordx4 v[120:123], v[120:121], off offset:256
	v_mfma_f32_16x16x32_bf16 v[56:59], v[182:185], v[194:197], v[56:59]
	v_mfma_f32_16x16x32_bf16 v[52:55], v[186:189], v[194:197], v[52:55]
	v_mfma_f32_16x16x32_bf16 v[48:51], v[190:193], v[194:197], v[48:51]
	ds_read_b128 v[246:249], v177 offset:16128
	s_waitcnt lgkmcnt(3)
	v_mfma_f32_16x16x32_bf16 v[44:47], v[178:181], v[198:201], v[44:47]
	s_waitcnt vmcnt(7)
	ds_write_b128 v253, v[124:127]
	v_mfma_f32_16x16x32_bf16 v[40:43], v[182:185], v[198:201], v[40:43]
	v_mfma_f32_16x16x32_bf16 v[36:39], v[186:189], v[198:201], v[36:39]
	v_lshl_add_u64 v[124:125], s[22:23], 0, v[168:169]
	s_nop 0
	global_load_dwordx4 v[124:127], v[124:125], off offset:256
	v_mfma_f32_16x16x32_bf16 v[32:35], v[190:193], v[198:201], v[32:35]
	ds_read_b128 v[194:197], v177 offset:64
	s_waitcnt lgkmcnt(3)
	v_mfma_f32_16x16x32_bf16 v[28:31], v[178:181], v[242:245], v[28:31]
	v_mfma_f32_16x16x32_bf16 v[24:27], v[182:185], v[242:245], v[24:27]
	v_mfma_f32_16x16x32_bf16 v[20:23], v[186:189], v[242:245], v[20:23]
	s_waitcnt vmcnt(7)
	ds_write_b128 v250, v[128:131] offset:36864
	v_mfma_f32_16x16x32_bf16 v[16:19], v[190:193], v[242:245], v[16:19]
	ds_read_b128 v[198:201], v177 offset:2368
	s_waitcnt lgkmcnt(4)
	v_mfma_f32_16x16x32_bf16 v[8:11], v[178:181], v[246:249], v[8:11]
	ds_read_b128 v[178:181], v202 offset:36928
	s_add_u32 s22, s8, s25
	s_addc_u32 s23, s9, 0
	v_lshl_add_u64 v[128:129], s[22:23], 0, v[162:163]
	s_nop 0
	global_load_dwordx4 v[128:131], v[128:129], off offset:256
	v_mfma_f32_16x16x32_bf16 v[4:7], v[182:185], v[246:249], v[4:7]
	ds_read_b128 v[182:185], v202 offset:39232
	v_mfma_f32_16x16x32_bf16 v[0:3], v[186:189], v[246:249], v[0:3]
	ds_read_b128 v[186:189], v202 offset:41536
	v_mfma_f32_16x16x32_bf16 v[12:15], v[190:193], v[246:249], v[12:15]
	ds_read_b128 v[190:193], v202 offset:43840
	ds_read_b128 v[242:245], v177 offset:4672
	s_waitcnt lgkmcnt(4)
	v_mfma_f32_16x16x32_bf16 v[156:159], v[178:181], v[194:197], v[156:159]
	s_waitcnt vmcnt(7)
	ds_write_b128 v251, v[132:135] offset:36864
	s_waitcnt lgkmcnt(4)
	v_mfma_f32_16x16x32_bf16 v[152:155], v[182:185], v[194:197], v[152:155]
	s_waitcnt lgkmcnt(3)
	v_mfma_f32_16x16x32_bf16 v[148:151], v[186:189], v[194:197], v[148:151]
	v_lshl_add_u64 v[132:133], s[22:23], 0, v[164:165]
	s_nop 0
	global_load_dwordx4 v[132:135], v[132:133], off offset:256
	s_waitcnt lgkmcnt(2)
	v_mfma_f32_16x16x32_bf16 v[144:147], v[190:193], v[194:197], v[144:147]
	ds_read_b128 v[246:249], v177 offset:6976
	v_mfma_f32_16x16x32_bf16 v[108:111], v[178:181], v[198:201], v[108:111]
	v_mfma_f32_16x16x32_bf16 v[104:107], v[182:185], v[198:201], v[104:107]
	v_mfma_f32_16x16x32_bf16 v[100:103], v[186:189], v[198:201], v[100:103]
	s_waitcnt vmcnt(7)
	ds_write_b128 v252, v[136:139] offset:36864
	v_mfma_f32_16x16x32_bf16 v[96:99], v[190:193], v[198:201], v[96:99]
	ds_read_b128 v[194:197], v177 offset:9280
	s_waitcnt lgkmcnt(4)
	v_mfma_f32_16x16x32_bf16 v[92:95], v[178:181], v[242:245], v[92:95]
	v_lshl_add_u64 v[136:137], s[22:23], 0, v[166:167]
	s_nop 0
	global_load_dwordx4 v[136:139], v[136:137], off offset:256
	v_mfma_f32_16x16x32_bf16 v[88:91], v[182:185], v[242:245], v[88:91]
	v_mfma_f32_16x16x32_bf16 v[84:87], v[186:189], v[242:245], v[84:87]
	v_mfma_f32_16x16x32_bf16 v[80:83], v[190:193], v[242:245], v[80:83]
	ds_read_b128 v[198:201], v177 offset:11584
	s_waitcnt lgkmcnt(3)
	v_mfma_f32_16x16x32_bf16 v[76:79], v[178:181], v[246:249], v[76:79]
	s_waitcnt vmcnt(7)
	ds_write_b128 v253, v[140:143] offset:36864
	v_mfma_f32_16x16x32_bf16 v[72:75], v[182:185], v[246:249], v[72:75]
	v_mfma_f32_16x16x32_bf16 v[68:71], v[186:189], v[246:249], v[68:71]
	v_lshl_add_u64 v[140:141], s[22:23], 0, v[168:169]
	s_nop 0
	global_load_dwordx4 v[140:143], v[140:141], off offset:256
	v_mfma_f32_16x16x32_bf16 v[64:67], v[190:193], v[246:249], v[64:67]
	ds_read_b128 v[242:245], v177 offset:13888
	s_waitcnt lgkmcnt(3)
	v_mfma_f32_16x16x32_bf16 v[60:63], v[178:181], v[194:197], v[60:63]
	v_mfma_f32_16x16x32_bf16 v[56:59], v[182:185], v[194:197], v[56:59]
	v_mfma_f32_16x16x32_bf16 v[52:55], v[186:189], v[194:197], v[52:55]
	v_mfma_f32_16x16x32_bf16 v[48:51], v[190:193], v[194:197], v[48:51]
	ds_read_b128 v[246:249], v177 offset:16192
	s_waitcnt lgkmcnt(3)
	v_mfma_f32_16x16x32_bf16 v[44:47], v[178:181], v[198:201], v[44:47]
	v_mfma_f32_16x16x32_bf16 v[40:43], v[182:185], v[198:201], v[40:43]
	v_mfma_f32_16x16x32_bf16 v[36:39], v[186:189], v[198:201], v[36:39]
	v_mfma_f32_16x16x32_bf16 v[32:35], v[190:193], v[198:201], v[32:35]
	s_waitcnt lgkmcnt(0)
	s_barrier
; DI f32x4 mfma16(bf16x8 a, bf16x8 b, f32x4 c) { return __builtin_amdgcn_mfma_f32_16x16x32_bf16(a, b, c, 0, 0, 0); }
; template <int MI, int NJ, bool SWAP, class AP, class BP>
; DI void gemm_main(f32x4 (&acc)[MI][NJ], const AP& ap, int a_kstep, const BP& bp, int b_kstep, int nk, bf16_t* smem) {
;     ...
;   for (int kt = 0; kt < nk; ++kt) {
;     const int buf = kt & 1;
;     sstore(buf ^ 1);
;     gload(kt + 2 < nk ? kt + 2 : nk - 1);
;     __builtin_amdgcn_sched_barrier(0);
;     const bf16_t* As = smem + buf * L::STAGE + (wm * 16 * MI + l15) * LDT + quad * 8;
;     const bf16_t* Bs = smem + buf * L::STAGE + L::A_ELEMS + (wn * 16 * NJ + l15) * LDT + quad * 8;
; #pragma unroll
;     for (int ks = 0; ks < 2; ++ks) {
;       if (MI * NJ >= 32 && ks == 1) asm volatile("" ::: "memory");
;       bf16x8 b[NJ];
; #pragma unroll
;       for (int j = 0; j < NJ; ++j) b[j] = *(const bf16x8*)(Bs + j * 16 * LDT + ks * 32);
; #pragma unroll
;       for (int i = 0; i < MI; ++i) {
;         const bf16x8 a = *(const bf16x8*)(As + i * 16 * LDT + ks * 32);
; #pragma unroll
;         for (int j = 0; j < NJ; ++j) acc[i][j] = SWAP ? mfma16(b[j], a, acc[i][j]) : mfma16(a, b[j], acc[i][j]);
;       }
	s_add_i32 s21, s21, 1
	s_cmp_lg_u32 s21, 44
	s_cbranch_scc0 .Lgm7_exit
	s_and_b32 s98, s21, 1
	s_mul_i32 s98, s98, 0x12000
	v_add3_u32 v202, s98, v160, v176
	v_add3_u32 v177, s98, v171, v176
	ds_read_b128 v[194:197], v177
	ds_read_b128 v[198:201], v177 offset:2304
	v_mfma_f32_16x16x32_bf16 v[28:31], v[178:181], v[242:245], v[28:31]
	v_mfma_f32_16x16x32_bf16 v[8:11], v[178:181], v[246:249], v[8:11]
	ds_read_b128 v[178:181], v202 offset:36864
	v_mfma_f32_16x16x32_bf16 v[24:27], v[182:185], v[242:245], v[24:27]
	v_mfma_f32_16x16x32_bf16 v[4:7], v[182:185], v[246:249], v[4:7]
	ds_read_b128 v[182:185], v202 offset:39168
	v_mfma_f32_16x16x32_bf16 v[20:23], v[186:189], v[242:245], v[20:23]
	v_mfma_f32_16x16x32_bf16 v[0:3], v[186:189], v[246:249], v[0:3]
	ds_read_b128 v[186:189], v202 offset:41472
	v_mfma_f32_16x16x32_bf16 v[16:19], v[190:193], v[242:245], v[16:19]
	v_mfma_f32_16x16x32_bf16 v[12:15], v[190:193], v[246:249], v[12:15]
	ds_read_b128 v[190:193], v202 offset:43776
	s_branch .Lgm7_main

; DI f32x4 mfma16(bf16x8 a, bf16x8 b, f32x4 c) { return __builtin_amdgcn_mfma_f32_16x16x32_bf16(a, b, c, 0, 0, 0); }
; template <int MI, int NJ, bool SWAP, class AP, class BP>
; DI void gemm_main(f32x4 (&acc)[MI][NJ], const AP& ap, int a_kstep, const BP& bp, int b_kstep, int nk, bf16_t* smem) {
;     ...
;   auto gload = [&](int kt) {
;     const bf16_t* ab = ap.base + (size_t)kt * a_kstep; const bf16_t* bb = bp.base + (size_t)kt * b_kstep;
; #pragma unroll
;     for (int i = 0; i < CA; ++i) ra[i] = *(const u32x4*)(ab + pa[i]);
; #pragma unroll
;     for (int i = 0; i < CB; ++i) rb[i] = *(const u32x4*)(bb + pb[i]);
;   };
;   auto sstore = [&](int buf) {
;     bf16_t* As = smem + buf * L::STAGE; bf16_t* Bs = As + L::A_ELEMS;
; #pragma unroll
;     for (int i = 0; i < CA; ++i) { const int c = tid + NTHR * i; *(u32x4*)(As + (c >> 3) * LDT + (c & 7) * 8) = oka[i] ? ra[i] : (u32x4){0u, 0u, 0u, 0u}; }
; #pragma unroll
;     for (int i = 0; i < CB; ++i) { const int c = tid + NTHR * i; *(u32x4*)(Bs + (c >> 3) * LDT + (c & 7) * 8) = rb[i]; }
;   };
;   gload(0); sstore(0); gload(nk > 1 ? 1 : 0); __syncthreads();
; #pragma unroll 1
;   for (int kt = 0; kt < nk; ++kt) {
;     const int buf = kt & 1;
;     sstore(buf ^ 1);
;     gload(kt + 2 < nk ? kt + 2 : nk - 1);
;     __builtin_amdgcn_sched_barrier(0);
;     const bf16_t* As = smem + buf * L::STAGE + (wm * 16 * MI + l15) * LDT + quad * 8;
;     const bf16_t* Bs = smem + buf * L::STAGE + L::A_ELEMS + (wn * 16 * NJ + l15) * LDT + quad * 8;
; #pragma unroll
;     for (int ks = 0; ks < 2; ++ks) {
;       if (MI * NJ >= 32 && ks == 1) asm volatile("" ::: "memory");
;       bf16x8 b[NJ];
; #pragma unroll
;       for (int j = 0; j < NJ; ++j) b[j] = *(const bf16x8*)(Bs + j * 16 * LDT + ks * 32);
; #pragma unroll
;       for (int i = 0; i < MI; ++i) {
;         const bf16x8 a = *(const bf16x8*)(As + i * 16 * LDT + ks * 32);
; #pragma unroll
;         for (int j = 0; j < NJ; ++j) acc[i][j] = SWAP ? mfma16(b[j], a, acc[i][j]) : mfma16(a, b[j], acc[i][j]);
;       }
;     }
;     __syncthreads();
;   }
.Lgm13_main:
	ds_read_b128 v[242:245], v177 offset:4608
	s_waitcnt lgkmcnt(4)
	v_mfma_f32_16x16x32_bf16 v[156:159], v[178:181], v[194:197], v[156:159]
	s_waitcnt lgkmcnt(3)
	v_mfma_f32_16x16x32_bf16 v[152:155], v[182:185], v[194:197], v[152:155]
	s_waitcnt lgkmcnt(2)
	v_mfma_f32_16x16x32_bf16 v[148:151], v[186:189], v[194:197], v[148:151]
	s_and_b32 s15, s1, 1
	s_min_u32 s16, s1, 13
	s_xor_b32 s17, s15, 1
	s_lshl_b32 s26, s16, 7
	s_mul_i32 s17, s17, 0x12000
	s_add_u32 s16, s2, s26
	v_add3_u32 v250, s17, v172, v170
	v_add3_u32 v251, s17, v174, v170
	v_add3_u32 v252, s17, v175, v170
	v_add3_u32 v253, s17, v176, v170
	s_addc_u32 s17, s3, 0
	s_waitcnt vmcnt(7)
	ds_write_b128 v250, v[112:115]
	s_waitcnt lgkmcnt(2)
	v_mfma_f32_16x16x32_bf16 v[144:147], v[190:193], v[194:197], v[144:147]
	ds_read_b128 v[246:249], v177 offset:6912
	v_mfma_f32_16x16x32_bf16 v[108:111], v[178:181], v[198:201], v[108:111]
	v_lshl_add_u64 v[112:113], s[16:17], 0, v[162:163]
	s_nop 0
	global_load_dwordx4 v[112:115], v[112:113], off offset:256
	v_mfma_f32_16x16x32_bf16 v[104:107], v[182:185], v[198:201], v[104:107]
	v_mfma_f32_16x16x32_bf16 v[100:103], v[186:189], v[198:201], v[100:103]
	v_mfma_f32_16x16x32_bf16 v[96:99], v[190:193], v[198:201], v[96:99]
	ds_read_b128 v[194:197], v177 offset:9216
	s_waitcnt lgkmcnt(3)
	v_mfma_f32_16x16x32_bf16 v[92:95], v[178:181], v[242:245], v[92:95]
	s_waitcnt vmcnt(7)
	ds_write_b128 v251, v[116:119]
	v_mfma_f32_16x16x32_bf16 v[88:91], v[182:185], v[242:245], v[88:91]
	v_mfma_f32_16x16x32_bf16 v[84:87], v[186:189], v[242:245], v[84:87]
	v_lshl_add_u64 v[116:117], s[16:17], 0, v[164:165]
	s_nop 0
	global_load_dwordx4 v[116:119], v[116:117], off offset:256
	v_mfma_f32_16x16x32_bf16 v[80:83], v[190:193], v[242:245], v[80:83]
	ds_read_b128 v[198:201], v177 offset:11520
	s_waitcnt lgkmcnt(3)
	v_mfma_f32_16x16x32_bf16 v[76:79], v[178:181], v[246:249], v[76:79]
	v_mfma_f32_16x16x32_bf16 v[72:75], v[182:185], v[246:249], v[72:75]
	v_mfma_f32_16x16x32_bf16 v[68:71], v[186:189], v[246:249], v[68:71]
	s_waitcnt vmcnt(7)
	ds_write_b128 v252, v[120:123]
	v_mfma_f32_16x16x32_bf16 v[64:67], v[190:193], v[246:249], v[64:67]
	ds_read_b128 v[242:245], v177 offset:13824
	s_waitcnt lgkmcnt(4)
	v_mfma_f32_16x16x32_bf16 v[60:63], v[178:181], v[194:197], v[60:63]
	v_lshl_add_u64 v[120:121], s[16:17], 0, v[166:167]
	s_nop 0
	global_load_dwordx4 v[120:123], v[120:121], off offset:256
	v_mfma_f32_16x16x32_bf16 v[56:59], v[182:185], v[194:197], v[56:59]
	v_mfma_f32_16x16x32_bf16 v[52:55], v[186:189], v[194:197], v[52:55]
	v_mfma_f32_16x16x32_bf16 v[48:51], v[190:193], v[194:197], v[48:51]
	ds_read_b128 v[246:249], v177 offset:16128
	s_waitcnt lgkmcnt(3)
	v_mfma_f32_16x16x32_bf16 v[44:47], v[178:181], v[198:201], v[44:47]
	s_waitcnt vmcnt(7)
	ds_write_b128 v253, v[124:127]
	v_mfma_f32_16x16x32_bf16 v[40:43], v[182:185], v[198:201], v[40:43]
	v_mfma_f32_16x16x32_bf16 v[36:39], v[186:189], v[198:201], v[36:39]
	v_lshl_add_u64 v[124:125], s[16:17], 0, v[168:169]
	s_nop 0
	global_load_dwordx4 v[124:127], v[124:125], off offset:256
	v_mfma_f32_16x16x32_bf16 v[32:35], v[190:193], v[198:201], v[32:35]
	ds_read_b128 v[194:197], v177 offset:64
	s_waitcnt lgkmcnt(3)
	v_mfma_f32_16x16x32_bf16 v[28:31], v[178:181], v[242:245], v[28:31]
	v_mfma_f32_16x16x32_bf16 v[24:27], v[182:185], v[242:245], v[24:27]
	v_mfma_f32_16x16x32_bf16 v[20:23], v[186:189], v[242:245], v[20:23]
	s_waitcnt vmcnt(7)
	ds_write_b128 v250, v[128:131] offset:36864
	v_mfma_f32_16x16x32_bf16 v[16:19], v[190:193], v[242:245], v[16:19]
	ds_read_b128 v[198:201], v177 offset:2368
	s_waitcnt lgkmcnt(4)
	v_mfma_f32_16x16x32_bf16 v[8:11], v[178:181], v[246:249], v[8:11]
	ds_read_b128 v[178:181], v202 offset:36928
	s_add_u32 s16, s12, s26
	s_addc_u32 s17, s13, 0
	v_lshl_add_u64 v[128:129], s[16:17], 0, v[162:163]
	s_nop 0
	global_load_dwordx4 v[128:131], v[128:129], off offset:256
	v_mfma_f32_16x16x32_bf16 v[4:7], v[182:185], v[246:249], v[4:7]
	ds_read_b128 v[182:185], v202 offset:39232
	v_mfma_f32_16x16x32_bf16 v[0:3], v[186:189], v[246:249], v[0:3]
	ds_read_b128 v[186:189], v202 offset:41536
	v_mfma_f32_16x16x32_bf16 v[12:15], v[190:193], v[246:249], v[12:15]
	ds_read_b128 v[190:193], v202 offset:43840
	ds_read_b128 v[242:245], v177 offset:4672
	s_waitcnt lgkmcnt(4)
	v_mfma_f32_16x16x32_bf16 v[156:159], v[178:181], v[194:197], v[156:159]
	s_waitcnt vmcnt(7)
	ds_write_b128 v251, v[132:135] offset:36864
	s_waitcnt lgkmcnt(4)
	v_mfma_f32_16x16x32_bf16 v[152:155], v[182:185], v[194:197], v[152:155]
	s_waitcnt lgkmcnt(3)
	v_mfma_f32_16x16x32_bf16 v[148:151], v[186:189], v[194:197], v[148:151]
	v_lshl_add_u64 v[132:133], s[16:17], 0, v[164:165]
	s_nop 0
	global_load_dwordx4 v[132:135], v[132:133], off offset:256
	s_waitcnt lgkmcnt(2)
	v_mfma_f32_16x16x32_bf16 v[144:147], v[190:193], v[194:197], v[144:147]
	ds_read_b128 v[246:249], v177 offset:6976
	v_mfma_f32_16x16x32_bf16 v[108:111], v[178:181], v[198:201], v[108:111]
	v_mfma_f32_16x16x32_bf16 v[104:107], v[182:185], v[198:201], v[104:107]
	v_mfma_f32_16x16x32_bf16 v[100:103], v[186:189], v[198:201], v[100:103]
	s_waitcnt vmcnt(7)
	ds_write_b128 v252, v[136:139] offset:36864
	v_mfma_f32_16x16x32_bf16 v[96:99], v[190:193], v[198:201], v[96:99]
	ds_read_b128 v[194:197], v177 offset:9280
	s_waitcnt lgkmcnt(4)
	v_mfma_f32_16x16x32_bf16 v[92:95], v[178:181], v[242:245], v[92:95]
	v_lshl_add_u64 v[136:137], s[16:17], 0, v[166:167]
	s_nop 0
	global_load_dwordx4 v[136:139], v[136:137], off offset:256
	v_mfma_f32_16x16x32_bf16 v[88:91], v[182:185], v[242:245], v[88:91]
	v_mfma_f32_16x16x32_bf16 v[84:87], v[186:189], v[242:245], v[84:87]
	v_mfma_f32_16x16x32_bf16 v[80:83], v[190:193], v[242:245], v[80:83]
	ds_read_b128 v[198:201], v177 offset:11584
	s_waitcnt lgkmcnt(3)
	v_mfma_f32_16x16x32_bf16 v[76:79], v[178:181], v[246:249], v[76:79]
	s_waitcnt vmcnt(7)
	ds_write_b128 v253, v[140:143] offset:36864
	v_mfma_f32_16x16x32_bf16 v[72:75], v[182:185], v[246:249], v[72:75]
	v_mfma_f32_16x16x32_bf16 v[68:71], v[186:189], v[246:249], v[68:71]
	v_lshl_add_u64 v[140:141], s[16:17], 0, v[168:169]
	s_nop 0
	global_load_dwordx4 v[140:143], v[140:141], off offset:256
	v_mfma_f32_16x16x32_bf16 v[64:67], v[190:193], v[246:249], v[64:67]
	ds_read_b128 v[242:245], v177 offset:13888
	s_waitcnt lgkmcnt(3)
	v_mfma_f32_16x16x32_bf16 v[60:63], v[178:181], v[194:197], v[60:63]
	v_mfma_f32_16x16x32_bf16 v[56:59], v[182:185], v[194:197], v[56:59]
	v_mfma_f32_16x16x32_bf16 v[52:55], v[186:189], v[194:197], v[52:55]
	v_mfma_f32_16x16x32_bf16 v[48:51], v[190:193], v[194:197], v[48:51]
	ds_read_b128 v[246:249], v177 offset:16192
	s_waitcnt lgkmcnt(3)
	v_mfma_f32_16x16x32_bf16 v[44:47], v[178:181], v[198:201], v[44:47]
	v_mfma_f32_16x16x32_bf16 v[40:43], v[182:185], v[198:201], v[40:43]
	v_mfma_f32_16x16x32_bf16 v[36:39], v[186:189], v[198:201], v[36:39]
	v_mfma_f32_16x16x32_bf16 v[32:35], v[190:193], v[198:201], v[32:35]
	s_waitcnt lgkmcnt(0)
	s_barrier
; DI f32x4 mfma16(bf16x8 a, bf16x8 b, f32x4 c) { return __builtin_amdgcn_mfma_f32_16x16x32_bf16(a, b, c, 0, 0, 0); }
; template <int MI, int NJ, bool SWAP, class AP, class BP>
; DI void gemm_main(f32x4 (&acc)[MI][NJ], const AP& ap, int a_kstep, const BP& bp, int b_kstep, int nk, bf16_t* smem) {
;     ...
;   for (int kt = 0; kt < nk; ++kt) {
;     const int buf = kt & 1;
;     sstore(buf ^ 1);
;     gload(kt + 2 < nk ? kt + 2 : nk - 1);
;     __builtin_amdgcn_sched_barrier(0);
;     const bf16_t* As = smem + buf * L::STAGE + (wm * 16 * MI + l15) * LDT + quad * 8;
;     const bf16_t* Bs = smem + buf * L::STAGE + L::A_ELEMS + (wn * 16 * NJ + l15) * LDT + quad * 8;
; #pragma unroll
;     for (int ks = 0; ks < 2; ++ks) {
;       if (MI * NJ >= 32 && ks == 1) asm volatile("" ::: "memory");
;       bf16x8 b[NJ];
; #pragma unroll
;       for (int j = 0; j < NJ; ++j) b[j] = *(const bf16x8*)(Bs + j * 16 * LDT + ks * 32);
; #pragma unroll
;       for (int i = 0; i < MI; ++i) {
;         const bf16x8 a = *(const bf16x8*)(As + i * 16 * LDT + ks * 32);
; #pragma unroll
;         for (int j = 0; j < NJ; ++j) acc[i][j] = SWAP ? mfma16(b[j], a, acc[i][j]) : mfma16(a, b[j], acc[i][j]);
;       }
	s_add_i32 s1, s1, 1
	s_cmp_lg_u32 s1, 16
	s_cbranch_scc0 .Lgm13_exit
	s_and_b32 s98, s1, 1
	s_mul_i32 s98, s98, 0x12000
	v_add3_u32 v202, s98, v160, v173
	v_add3_u32 v177, s98, v171, v173
	ds_read_b128 v[194:197], v177
	ds_read_b128 v[198:201], v177 offset:2304
	v_mfma_f32_16x16x32_bf16 v[28:31], v[178:181], v[242:245], v[28:31]
	v_mfma_f32_16x16x32_bf16 v[8:11], v[178:181], v[246:249], v[8:11]
	ds_read_b128 v[178:181], v202 offset:36864
	v_mfma_f32_16x16x32_bf16 v[24:27], v[182:185], v[242:245], v[24:27]
	v_mfma_f32_16x16x32_bf16 v[4:7], v[182:185], v[246:249], v[4:7]
	ds_read_b128 v[182:185], v202 offset:39168
	v_mfma_f32_16x16x32_bf16 v[20:23], v[186:189], v[242:245], v[20:23]
	v_mfma_f32_16x16x32_bf16 v[0:3], v[186:189], v[246:249], v[0:3]
	ds_read_b128 v[186:189], v202 offset:41472
	v_mfma_f32_16x16x32_bf16 v[16:19], v[190:193], v[242:245], v[16:19]
	v_mfma_f32_16x16x32_bf16 v[12:15], v[190:193], v[246:249], v[12:15]
	ds_read_b128 v[190:193], v202 offset:43776
	s_branch .Lgm13_main

; DI f32x4 mfma16(bf16x8 a, bf16x8 b, f32x4 c) { return __builtin_amdgcn_mfma_f32_16x16x32_bf16(a, b, c, 0, 0, 0); }
; template <int MI, int NJ, bool SWAP, class AP, class BP>
; DI void gemm_main(f32x4 (&acc)[MI][NJ], const AP& ap, int a_kstep, const BP& bp, int b_kstep, int nk, bf16_t* smem) {
;     ...
;   auto gload = [&](int kt) {
;     const bf16_t* ab = ap.base + (size_t)kt * a_kstep; const bf16_t* bb = bp.base + (size_t)kt * b_kstep;
; #pragma unroll
;     for (int i = 0; i < CA; ++i) ra[i] = *(const u32x4*)(ab + pa[i]);
; #pragma unroll
;     for (int i = 0; i < CB; ++i) rb[i] = *(const u32x4*)(bb + pb[i]);
;   };
;   auto sstore = [&](int buf) {
;     bf16_t* As = smem + buf * L::STAGE; bf16_t* Bs = As + L::A_ELEMS;
; #pragma unroll
;     for (int i = 0; i < CA; ++i) { const int c = tid + NTHR * i; *(u32x4*)(As + (c >> 3) * LDT + (c & 7) * 8) = oka[i] ? ra[i] : (u32x4){0u, 0u, 0u, 0u}; }
; #pragma unroll
;     for (int i = 0; i < CB; ++i) { const int c = tid + NTHR * i; *(u32x4*)(Bs + (c >> 3) * LDT + (c & 7) * 8) = rb[i]; }
;   };
;   gload(0); sstore(0); gload(nk > 1 ? 1 : 0); __syncthreads();
; #pragma unroll 1
;   for (int kt = 0; kt < nk; ++kt) {
;     const int buf = kt & 1;
;     sstore(buf ^ 1);
;     gload(kt + 2 < nk ? kt + 2 : nk - 1);
;     __builtin_amdgcn_sched_barrier(0);
;     const bf16_t* As = smem + buf * L::STAGE + (wm * 16 * MI + l15) * LDT + quad * 8;
;     const bf16_t* Bs = smem + buf * L::STAGE + L::A_ELEMS + (wn * 16 * NJ + l15) * LDT + quad * 8;
; #pragma unroll
;     for (int ks = 0; ks < 2; ++ks) {
;       if (MI * NJ >= 32 && ks == 1) asm volatile("" ::: "memory");
;       bf16x8 b[NJ];
; #pragma unroll
;       for (int j = 0; j < NJ; ++j) b[j] = *(const bf16x8*)(Bs + j * 16 * LDT + ks * 32);
; #pragma unroll
;       for (int i = 0; i < MI; ++i) {
;         const bf16x8 a = *(const bf16x8*)(As + i * 16 * LDT + ks * 32);
; #pragma unroll
;         for (int j = 0; j < NJ; ++j) acc[i][j] = SWAP ? mfma16(b[j], a, acc[i][j]) : mfma16(a, b[j], acc[i][j]);
;       }
;     }
;     __syncthreads();
;   }
.Lgm15_main:
	ds_read_b128 v[242:245], v177 offset:4608
	s_waitcnt lgkmcnt(4)
	v_mfma_f32_16x16x32_bf16 v[156:159], v[178:181], v[194:197], v[156:159]
	s_waitcnt lgkmcnt(3)
	v_mfma_f32_16x16x32_bf16 v[152:155], v[182:185], v[194:197], v[152:155]
	s_waitcnt lgkmcnt(2)
	v_mfma_f32_16x16x32_bf16 v[148:151], v[186:189], v[194:197], v[148:151]
	s_and_b32 s17, s16, 1
	s_min_u32 s18, s16, 41
	s_xor_b32 s19, s17, 1
	s_lshl_b32 s20, s18, 7
	s_mul_i32 s19, s19, 0x12000
	s_add_u32 s18, s2, s20
	v_add3_u32 v250, s19, v172, v170
	v_add3_u32 v251, s19, v173, v170
	v_add3_u32 v252, s19, v174, v170
	v_add3_u32 v253, s19, v175, v170
	s_addc_u32 s19, s3, 0
	s_waitcnt vmcnt(7)
	ds_write_b128 v250, v[112:115]
	s_waitcnt lgkmcnt(2)
	v_mfma_f32_16x16x32_bf16 v[144:147], v[190:193], v[194:197], v[144:147]
	ds_read_b128 v[246:249], v177 offset:6912
	v_mfma_f32_16x16x32_bf16 v[108:111], v[178:181], v[198:201], v[108:111]
	v_lshl_add_u64 v[112:113], s[18:19], 0, v[162:163]
	s_nop 0
	global_load_dwordx4 v[112:115], v[112:113], off offset:256
	v_mfma_f32_16x16x32_bf16 v[104:107], v[182:185], v[198:201], v[104:107]
	v_mfma_f32_16x16x32_bf16 v[100:103], v[186:189], v[198:201], v[100:103]
	v_mfma_f32_16x16x32_bf16 v[96:99], v[190:193], v[198:201], v[96:99]
	ds_read_b128 v[194:197], v177 offset:9216
	s_waitcnt lgkmcnt(3)
	v_mfma_f32_16x16x32_bf16 v[92:95], v[178:181], v[242:245], v[92:95]
	s_waitcnt vmcnt(7)
	ds_write_b128 v251, v[116:119]
	v_mfma_f32_16x16x32_bf16 v[88:91], v[182:185], v[242:245], v[88:91]
	v_mfma_f32_16x16x32_bf16 v[84:87], v[186:189], v[242:245], v[84:87]
	v_lshl_add_u64 v[116:117], s[18:19], 0, v[164:165]
	s_nop 0
	global_load_dwordx4 v[116:119], v[116:117], off offset:256
	v_mfma_f32_16x16x32_bf16 v[80:83], v[190:193], v[242:245], v[80:83]
	ds_read_b128 v[198:201], v177 offset:11520
	s_waitcnt lgkmcnt(3)
	v_mfma_f32_16x16x32_bf16 v[76:79], v[178:181], v[246:249], v[76:79]
	v_mfma_f32_16x16x32_bf16 v[72:75], v[182:185], v[246:249], v[72:75]
	v_mfma_f32_16x16x32_bf16 v[68:71], v[186:189], v[246:249], v[68:71]
	s_waitcnt vmcnt(7)
	ds_write_b128 v252, v[120:123]
	v_mfma_f32_16x16x32_bf16 v[64:67], v[190:193], v[246:249], v[64:67]
	ds_read_b128 v[242:245], v177 offset:13824
	s_waitcnt lgkmcnt(4)
	v_mfma_f32_16x16x32_bf16 v[60:63], v[178:181], v[194:197], v[60:63]
	v_lshl_add_u64 v[120:121], s[18:19], 0, v[166:167]
	s_nop 0
	global_load_dwordx4 v[120:123], v[120:121], off offset:256
	v_mfma_f32_16x16x32_bf16 v[56:59], v[182:185], v[194:197], v[56:59]
	v_mfma_f32_16x16x32_bf16 v[52:55], v[186:189], v[194:197], v[52:55]
	v_mfma_f32_16x16x32_bf16 v[48:51], v[190:193], v[194:197], v[48:51]
	ds_read_b128 v[246:249], v177 offset:16128
	s_waitcnt lgkmcnt(3)
	v_mfma_f32_16x16x32_bf16 v[44:47], v[178:181], v[198:201], v[44:47]
	s_waitcnt vmcnt(7)
	ds_write_b128 v253, v[124:127]
	v_mfma_f32_16x16x32_bf16 v[40:43], v[182:185], v[198:201], v[40:43]
	v_mfma_f32_16x16x32_bf16 v[36:39], v[186:189], v[198:201], v[36:39]
	v_lshl_add_u64 v[124:125], s[18:19], 0, v[168:169]
	s_nop 0
	global_load_dwordx4 v[124:127], v[124:125], off offset:256
	v_mfma_f32_16x16x32_bf16 v[32:35], v[190:193], v[198:201], v[32:35]
	ds_read_b128 v[194:197], v177 offset:64
	s_waitcnt lgkmcnt(3)
	v_mfma_f32_16x16x32_bf16 v[28:31], v[178:181], v[242:245], v[28:31]
	v_mfma_f32_16x16x32_bf16 v[24:27], v[182:185], v[242:245], v[24:27]
	v_mfma_f32_16x16x32_bf16 v[20:23], v[186:189], v[242:245], v[20:23]
	s_waitcnt vmcnt(7)
	ds_write_b128 v250, v[128:131] offset:36864
	v_mfma_f32_16x16x32_bf16 v[16:19], v[190:193], v[242:245], v[16:19]
	ds_read_b128 v[198:201], v177 offset:2368
	s_waitcnt lgkmcnt(4)
	v_mfma_f32_16x16x32_bf16 v[8:11], v[178:181], v[246:249], v[8:11]
	ds_read_b128 v[178:181], v202 offset:36928
	s_add_u32 s18, s4, s20
	s_addc_u32 s19, s5, 0
	v_lshl_add_u64 v[128:129], s[18:19], 0, v[162:163]
	s_nop 0
	global_load_dwordx4 v[128:131], v[128:129], off offset:256
	v_mfma_f32_16x16x32_bf16 v[4:7], v[182:185], v[246:249], v[4:7]
	ds_read_b128 v[182:185], v202 offset:39232
	v_mfma_f32_16x16x32_bf16 v[0:3], v[186:189], v[246:249], v[0:3]
	ds_read_b128 v[186:189], v202 offset:41536
	v_mfma_f32_16x16x32_bf16 v[12:15], v[190:193], v[246:249], v[12:15]
	ds_read_b128 v[190:193], v202 offset:43840
	ds_read_b128 v[242:245], v177 offset:4672
	s_waitcnt lgkmcnt(4)
	v_mfma_f32_16x16x32_bf16 v[156:159], v[178:181], v[194:197], v[156:159]
	s_waitcnt vmcnt(7)
	ds_write_b128 v251, v[132:135] offset:36864
	s_waitcnt lgkmcnt(4)
	v_mfma_f32_16x16x32_bf16 v[152:155], v[182:185], v[194:197], v[152:155]
	s_waitcnt lgkmcnt(3)
	v_mfma_f32_16x16x32_bf16 v[148:151], v[186:189], v[194:197], v[148:151]
	v_lshl_add_u64 v[132:133], s[18:19], 0, v[164:165]
	s_nop 0
	global_load_dwordx4 v[132:135], v[132:133], off offset:256
	s_waitcnt lgkmcnt(2)
	v_mfma_f32_16x16x32_bf16 v[144:147], v[190:193], v[194:197], v[144:147]
	ds_read_b128 v[246:249], v177 offset:6976
	v_mfma_f32_16x16x32_bf16 v[108:111], v[178:181], v[198:201], v[108:111]
	v_mfma_f32_16x16x32_bf16 v[104:107], v[182:185], v[198:201], v[104:107]
	v_mfma_f32_16x16x32_bf16 v[100:103], v[186:189], v[198:201], v[100:103]
	s_waitcnt vmcnt(7)
	ds_write_b128 v252, v[136:139] offset:36864
	v_mfma_f32_16x16x32_bf16 v[96:99], v[190:193], v[198:201], v[96:99]
	ds_read_b128 v[194:197], v177 offset:9280
	s_waitcnt lgkmcnt(4)
	v_mfma_f32_16x16x32_bf16 v[92:95], v[178:181], v[242:245], v[92:95]
	v_lshl_add_u64 v[136:137], s[18:19], 0, v[166:167]
	s_nop 0
	global_load_dwordx4 v[136:139], v[136:137], off offset:256
	v_mfma_f32_16x16x32_bf16 v[88:91], v[182:185], v[242:245], v[88:91]
	v_mfma_f32_16x16x32_bf16 v[84:87], v[186:189], v[242:245], v[84:87]
	v_mfma_f32_16x16x32_bf16 v[80:83], v[190:193], v[242:245], v[80:83]
	ds_read_b128 v[198:201], v177 offset:11584
	s_waitcnt lgkmcnt(3)
	v_mfma_f32_16x16x32_bf16 v[76:79], v[178:181], v[246:249], v[76:79]
	s_waitcnt vmcnt(7)
	ds_write_b128 v253, v[140:143] offset:36864
	v_mfma_f32_16x16x32_bf16 v[72:75], v[182:185], v[246:249], v[72:75]
	v_mfma_f32_16x16x32_bf16 v[68:71], v[186:189], v[246:249], v[68:71]
	v_lshl_add_u64 v[140:141], s[18:19], 0, v[168:169]
	s_nop 0
	global_load_dwordx4 v[140:143], v[140:141], off offset:256
	v_mfma_f32_16x16x32_bf16 v[64:67], v[190:193], v[246:249], v[64:67]
	ds_read_b128 v[242:245], v177 offset:13888
	s_waitcnt lgkmcnt(3)
	v_mfma_f32_16x16x32_bf16 v[60:63], v[178:181], v[194:197], v[60:63]
	v_mfma_f32_16x16x32_bf16 v[56:59], v[182:185], v[194:197], v[56:59]
	v_mfma_f32_16x16x32_bf16 v[52:55], v[186:189], v[194:197], v[52:55]
	v_mfma_f32_16x16x32_bf16 v[48:51], v[190:193], v[194:197], v[48:51]
	ds_read_b128 v[246:249], v177 offset:16192
	s_waitcnt lgkmcnt(3)
	v_mfma_f32_16x16x32_bf16 v[44:47], v[178:181], v[198:201], v[44:47]
	v_mfma_f32_16x16x32_bf16 v[40:43], v[182:185], v[198:201], v[40:43]
	v_mfma_f32_16x16x32_bf16 v[36:39], v[186:189], v[198:201], v[36:39]
	v_mfma_f32_16x16x32_bf16 v[32:35], v[190:193], v[198:201], v[32:35]
	s_waitcnt lgkmcnt(0)
	s_barrier
; DI f32x4 mfma16(bf16x8 a, bf16x8 b, f32x4 c) { return __builtin_amdgcn_mfma_f32_16x16x32_bf16(a, b, c, 0, 0, 0); }
; template <int MI, int NJ, bool SWAP, class AP, class BP>
; DI void gemm_main(f32x4 (&acc)[MI][NJ], const AP& ap, int a_kstep, const BP& bp, int b_kstep, int nk, bf16_t* smem) {
;     ...
;   for (int kt = 0; kt < nk; ++kt) {
;     const int buf = kt & 1;
;     sstore(buf ^ 1);
;     gload(kt + 2 < nk ? kt + 2 : nk - 1);
;     __builtin_amdgcn_sched_barrier(0);
;     const bf16_t* As = smem + buf * L::STAGE + (wm * 16 * MI + l15) * LDT + quad * 8;
;     const bf16_t* Bs = smem + buf * L::STAGE + L::A_ELEMS + (wn * 16 * NJ + l15) * LDT + quad * 8;
; #pragma unroll
;     for (int ks = 0; ks < 2; ++ks) {
;       if (MI * NJ >= 32 && ks == 1) asm volatile("" ::: "memory");
;       bf16x8 b[NJ];
; #pragma unroll
;       for (int j = 0; j < NJ; ++j) b[j] = *(const bf16x8*)(Bs + j * 16 * LDT + ks * 32);
; #pragma unroll
;       for (int i = 0; i < MI; ++i) {
;         const bf16x8 a = *(const bf16x8*)(As + i * 16 * LDT + ks * 32);
; #pragma unroll
;         for (int j = 0; j < NJ; ++j) acc[i][j] = SWAP ? mfma16(b[j], a, acc[i][j]) : mfma16(a, b[j], acc[i][j]);
;       }
	s_add_i32 s16, s16, 1
	s_cmp_lg_u32 s16, 44
	s_cbranch_scc0 .Lgm15_exit
	s_and_b32 s98, s16, 1
	s_mul_i32 s98, s98, 0x12000
	v_add3_u32 v202, s98, v160, v176
	v_add3_u32 v177, s98, v171, v176
	ds_read_b128 v[194:197], v177
	ds_read_b128 v[198:201], v177 offset:2304
	v_mfma_f32_16x16x32_bf16 v[28:31], v[178:181], v[242:245], v[28:31]
	v_mfma_f32_16x16x32_bf16 v[8:11], v[178:181], v[246:249], v[8:11]
	ds_read_b128 v[178:181], v202 offset:36864
	v_mfma_f32_16x16x32_bf16 v[24:27], v[182:185], v[242:245], v[24:27]
	v_mfma_f32_16x16x32_bf16 v[4:7], v[182:185], v[246:249], v[4:7]
	ds_read_b128 v[182:185], v202 offset:39168
	v_mfma_f32_16x16x32_bf16 v[20:23], v[186:189], v[242:245], v[20:23]
	v_mfma_f32_16x16x32_bf16 v[0:3], v[186:189], v[246:249], v[0:3]
	ds_read_b128 v[186:189], v202 offset:41472
	v_mfma_f32_16x16x32_bf16 v[16:19], v[190:193], v[242:245], v[16:19]
	v_mfma_f32_16x16x32_bf16 v[12:15], v[190:193], v[246:249], v[12:15]
	ds_read_b128 v[190:193], v202 offset:43776
	s_branch .Lgm15_main
